# v23 + FF1/FF2 MFMA order: same-accumulator k0,k1 pairs back to back (accumulation order per accumulator unchanged)
# speedup vs baseline: 1.0040x; 1.0040x over previous
; #define PG8_STAGE(bufoff, gbase, voff) do { _Pragma("unroll") for (int _i = 0; _i < 2; ++_i) \
;         __builtin_amdgcn_global_load_lds((const unsigned*)((const char*)(gbase) + (voff)[_i]), (PG8_LAS unsigned*)(lds + (bufoff) + ldsw + _i * 8192), 16, 0, 0); } while (0)
; #define PG8_LDA(dst, b, h) do { _Pragma("unroll") for (int m = 0; m < 4; ++m) _Pragma("unroll") for (int k = 0; k < 2; ++k) dst[m][k] = *(const PG8_LAS bf16x8*)(lds + PG8_SA(b, h) + aoff + m * 2048 + k * 1024); } while (0)
; #define PG8_LDB(dst, b, h) do { _Pragma("unroll") for (int n = 0; n < 2; ++n) _Pragma("unroll") for (int k = 0; k < 2; ++k) dst[n][k] = *(const PG8_LAS bf16x8*)(lds + PG8_SB(b, h) + boff + n * 2048 + k * 1024); } while (0)
; #define PG8_MMA(ai, bj, At, Bt) do { __builtin_amdgcn_s_setprio(1); _Pragma("unroll") for (int m = 0; m < 4; ++m) _Pragma("unroll") for (int n = 0; n < 2; ++n) _Pragma("unroll") for (int k = 0; k < 2; ++k) \
;         acc[ai][bj][m][n] = __builtin_amdgcn_mfma_f32_16x16x32_bf16(Bt[n][k], At[m][k], acc[ai][bj][m][n], 0, 0, 0); __builtin_amdgcn_s_setprio(0); } while (0)
; #define PG8_BAR __builtin_amdgcn_s_barrier()
; template <class Epi, class Sched, bool ALIGN_EPI = false, bool SP2 = false>
; __device__ __forceinline__ void gemm_phase(PG8_LAS unsigned char* lds, const Gemm g, const Sched& S, const Epi& E) {
;     ...
;             if constexpr (SP2) {
;             PG8_LDB(B0, 0, 0); PG8_LDB(B1, 0, 1); PG8_SCHED; PG8_LDA(At, 0, 0); PG8_STAGE(PG8_SA(1, 1), a1 + hstep, voffA);
;             PG8_WAIT_V(8); PG8_WAIT_L(0); PG8_BAR; PG8_MMA(0, 0, At, B0); PG8_MMA(0, 1, At, B1); PG8_BAR; PG8_SCHED;
;             PG8_LDA(At, 0, 1); PG8_STAGE(PG8_SB(0, 0), b2, voffB); PG8_STAGE(PG8_SB(0, 1), b2 + hstep, voffB); PG8_STAGE(PG8_SA(0, 0), a2, voffA);
;             PG8_WAIT_V(8); PG8_WAIT_L(0); PG8_BAR; PG8_MMA(1, 0, At, B0); PG8_MMA(1, 1, At, B1); PG8_BAR; PG8_SCHED;
;             PG8_LDB(B0, 1, 0); PG8_LDB(B1, 1, 1); PG8_SCHED; PG8_LDA(At, 1, 0); PG8_STAGE(PG8_SA(0, 1), a2 + hstep, voffA);
;             PG8_WAIT_V(8); PG8_WAIT_L(0); PG8_BAR; PG8_MMA(0, 0, At, B0); PG8_MMA(0, 1, At, B1); PG8_BAR; PG8_SCHED;
;             PG8_LDA(At, 1, 1); PG8_STAGE(PG8_SB(1, 0), b3, voffB); PG8_STAGE(PG8_SB(1, 1), b3 + hstep, voffB); PG8_STAGE(PG8_SA(1, 0), a3, voffA);
;             PG8_WAIT_V(8); PG8_WAIT_L(0); PG8_BAR; PG8_MMA(1, 0, At, B0); PG8_MMA(1, 1, At, B1); PG8_BAR; PG8_SCHED;
.LBB0_1251:
	ds_read_b128 v[130:133], v177
	ds_read_b128 v[134:137], v177 offset:1024
	ds_read_b128 v[138:141], v177 offset:2048
	ds_read_b128 v[142:145], v177 offset:3072
	ds_read_b128 v[162:165], v178
	ds_read_b128 v[180:183], v178 offset:1024
	ds_read_b128 v[184:187], v178 offset:2048
	ds_read_b128 v[188:191], v178 offset:3072
	s_add_u32 s40, s36, 0xfff00080
	s_addc_u32 s41, s37, -1
	s_cmp_eq_u32 s58, 60
	s_cselect_b32 s43, s15, s41
	s_cselect_b32 s42, s17, s40
	s_cselect_b32 s41, s54, s57
	s_cselect_b32 s40, s55, s56
	ds_read_b128 v[196:199], v179
	ds_read_b128 v[200:203], v179 offset:1024
	ds_read_b128 v[204:207], v179 offset:2048
	ds_read_b128 v[208:211], v179 offset:3072
	ds_read_b128 v[212:215], v179 offset:4096
	ds_read_b128 v[220:223], v179 offset:5120
	ds_read_b128 v[224:227], v179 offset:6144
	ds_read_b128 v[228:231], v179 offset:7168
	s_add_i32 m0, s24, 0xc000
	s_nop 0
	global_load_lds_dwordx4 v146, s[36:37]
	s_add_i32 m0, s24, 0xe000
	s_nop 0
	global_load_lds_dwordx4 v150, s[36:37]
	s_waitcnt lgkmcnt(0)
	s_setprio 1
	v_mfma_f32_16x16x32_bf16 v[126:129], v[130:133], v[196:199], v[126:129]
	v_mfma_f32_16x16x32_bf16 v[126:129], v[134:137], v[200:203], v[126:129]
	v_mfma_f32_16x16x32_bf16 v[122:125], v[138:141], v[196:199], v[122:125]
	v_mfma_f32_16x16x32_bf16 v[122:125], v[142:145], v[200:203], v[122:125]
	v_mfma_f32_16x16x32_bf16 v[110:113], v[130:133], v[204:207], v[110:113]
	v_mfma_f32_16x16x32_bf16 v[110:113], v[134:137], v[208:211], v[110:113]
	v_mfma_f32_16x16x32_bf16 v[106:109], v[138:141], v[204:207], v[106:109]
	v_mfma_f32_16x16x32_bf16 v[106:109], v[142:145], v[208:211], v[106:109]
	v_mfma_f32_16x16x32_bf16 v[94:97], v[130:133], v[212:215], v[94:97]
	v_mfma_f32_16x16x32_bf16 v[94:97], v[134:137], v[220:223], v[94:97]
	v_mfma_f32_16x16x32_bf16 v[90:93], v[138:141], v[212:215], v[90:93]
	v_mfma_f32_16x16x32_bf16 v[90:93], v[142:145], v[220:223], v[90:93]
	v_mfma_f32_16x16x32_bf16 v[78:81], v[130:133], v[224:227], v[78:81]
	v_mfma_f32_16x16x32_bf16 v[78:81], v[134:137], v[228:231], v[78:81]
	v_mfma_f32_16x16x32_bf16 v[74:77], v[138:141], v[224:227], v[74:77]
	v_mfma_f32_16x16x32_bf16 v[74:77], v[142:145], v[228:231], v[74:77]
	v_mfma_f32_16x16x32_bf16 v[118:121], v[162:165], v[196:199], v[118:121]
	v_mfma_f32_16x16x32_bf16 v[118:121], v[180:183], v[200:203], v[118:121]
	v_mfma_f32_16x16x32_bf16 v[114:117], v[184:187], v[196:199], v[114:117]
	v_mfma_f32_16x16x32_bf16 v[114:117], v[188:191], v[200:203], v[114:117]
	v_mfma_f32_16x16x32_bf16 v[102:105], v[162:165], v[204:207], v[102:105]
	v_mfma_f32_16x16x32_bf16 v[102:105], v[180:183], v[208:211], v[102:105]
	v_mfma_f32_16x16x32_bf16 v[98:101], v[184:187], v[204:207], v[98:101]
	v_mfma_f32_16x16x32_bf16 v[98:101], v[188:191], v[208:211], v[98:101]
	v_mfma_f32_16x16x32_bf16 v[86:89], v[162:165], v[212:215], v[86:89]
	v_mfma_f32_16x16x32_bf16 v[86:89], v[180:183], v[220:223], v[86:89]
	v_mfma_f32_16x16x32_bf16 v[82:85], v[184:187], v[212:215], v[82:85]
	v_mfma_f32_16x16x32_bf16 v[82:85], v[188:191], v[220:223], v[82:85]
	v_mfma_f32_16x16x32_bf16 v[70:73], v[162:165], v[224:227], v[70:73]
	v_mfma_f32_16x16x32_bf16 v[70:73], v[180:183], v[228:231], v[70:73]
	v_mfma_f32_16x16x32_bf16 v[66:69], v[184:187], v[224:227], v[66:69]
	v_mfma_f32_16x16x32_bf16 v[66:69], v[188:191], v[228:231], v[66:69]
	s_setprio 0
	s_waitcnt vmcnt(8)
	s_barrier
	ds_read_b128 v[196:199], v179 offset:16384
	ds_read_b128 v[200:203], v179 offset:17408
	ds_read_b128 v[204:207], v179 offset:18432
	ds_read_b128 v[208:211], v179 offset:19456
	ds_read_b128 v[212:215], v179 offset:20480
	ds_read_b128 v[220:223], v179 offset:21504
	ds_read_b128 v[224:227], v179 offset:22528
	ds_read_b128 v[228:231], v179 offset:23552
	s_add_u32 vcc_lo, s40, 0x100000
	s_addc_u32 vcc_hi, s41, 0
	s_add_i32 m0, s24, 0x10000
	s_nop 0
	global_load_lds_dwordx4 v148, s[40:41]
	s_add_i32 m0, s24, 0x12000
	s_nop 0
	global_load_lds_dwordx4 v152, s[40:41]
	s_add_i32 m0, s24, 0x14000
	s_nop 0
	global_load_lds_dwordx4 v148, vcc
	s_add_i32 m0, s24, 0x16000
	s_nop 0
	global_load_lds_dwordx4 v152, vcc
	s_mov_b32 m0, s24
	s_nop 0
	global_load_lds_dwordx4 v146, s[42:43]
	s_add_i32 m0, s24, 0x2000
	s_nop 0
	global_load_lds_dwordx4 v150, s[42:43]
	s_waitcnt lgkmcnt(0)
	s_setprio 1
	v_mfma_f32_16x16x32_bf16 v[62:65], v[130:133], v[196:199], v[62:65]
	v_mfma_f32_16x16x32_bf16 v[62:65], v[134:137], v[200:203], v[62:65]
	v_mfma_f32_16x16x32_bf16 v[58:61], v[138:141], v[196:199], v[58:61]
	v_mfma_f32_16x16x32_bf16 v[58:61], v[142:145], v[200:203], v[58:61]
	v_mfma_f32_16x16x32_bf16 v[46:49], v[130:133], v[204:207], v[46:49]
	v_mfma_f32_16x16x32_bf16 v[46:49], v[134:137], v[208:211], v[46:49]
	v_mfma_f32_16x16x32_bf16 v[42:45], v[138:141], v[204:207], v[42:45]
	v_mfma_f32_16x16x32_bf16 v[42:45], v[142:145], v[208:211], v[42:45]
	v_mfma_f32_16x16x32_bf16 v[30:33], v[130:133], v[212:215], v[30:33]
	v_mfma_f32_16x16x32_bf16 v[30:33], v[134:137], v[220:223], v[30:33]
	v_mfma_f32_16x16x32_bf16 v[26:29], v[138:141], v[212:215], v[26:29]
	v_mfma_f32_16x16x32_bf16 v[26:29], v[142:145], v[220:223], v[26:29]
	v_mfma_f32_16x16x32_bf16 v[14:17], v[130:133], v[224:227], v[14:17]
	v_mfma_f32_16x16x32_bf16 v[14:17], v[134:137], v[228:231], v[14:17]
	v_mfma_f32_16x16x32_bf16 v[10:13], v[138:141], v[224:227], v[10:13]
	v_mfma_f32_16x16x32_bf16 v[10:13], v[142:145], v[228:231], v[10:13]
	v_mfma_f32_16x16x32_bf16 v[54:57], v[162:165], v[196:199], v[54:57]
	v_mfma_f32_16x16x32_bf16 v[54:57], v[180:183], v[200:203], v[54:57]
	v_mfma_f32_16x16x32_bf16 v[50:53], v[184:187], v[196:199], v[50:53]
	v_mfma_f32_16x16x32_bf16 v[50:53], v[188:191], v[200:203], v[50:53]
	v_mfma_f32_16x16x32_bf16 v[38:41], v[162:165], v[204:207], v[38:41]
	v_mfma_f32_16x16x32_bf16 v[38:41], v[180:183], v[208:211], v[38:41]
	v_mfma_f32_16x16x32_bf16 v[34:37], v[184:187], v[204:207], v[34:37]
	v_mfma_f32_16x16x32_bf16 v[34:37], v[188:191], v[208:211], v[34:37]
	v_mfma_f32_16x16x32_bf16 v[22:25], v[162:165], v[212:215], v[22:25]
	v_mfma_f32_16x16x32_bf16 v[22:25], v[180:183], v[220:223], v[22:25]
	v_mfma_f32_16x16x32_bf16 v[18:21], v[184:187], v[212:215], v[18:21]
	v_mfma_f32_16x16x32_bf16 v[18:21], v[188:191], v[220:223], v[18:21]
	v_mfma_f32_16x16x32_bf16 v[6:9], v[162:165], v[224:227], v[6:9]
	v_mfma_f32_16x16x32_bf16 v[6:9], v[180:183], v[228:231], v[6:9]
	v_mfma_f32_16x16x32_bf16 v[2:5], v[184:187], v[224:227], v[2:5]
	v_mfma_f32_16x16x32_bf16 v[2:5], v[188:191], v[228:231], v[2:5]
	s_setprio 0
	s_waitcnt vmcnt(8)
	s_barrier
; #define PG8_STAGE(bufoff, gbase, voff) do { _Pragma("unroll") for (int _i = 0; _i < 2; ++_i) \
;         __builtin_amdgcn_global_load_lds((const unsigned*)((const char*)(gbase) + (voff)[_i]), (PG8_LAS unsigned*)(lds + (bufoff) + ldsw + _i * 8192), 16, 0, 0); } while (0)
; #define PG8_LDA(dst, b, h) do { _Pragma("unroll") for (int m = 0; m < 4; ++m) _Pragma("unroll") for (int k = 0; k < 2; ++k) dst[m][k] = *(const PG8_LAS bf16x8*)(lds + PG8_SA(b, h) + aoff + m * 2048 + k * 1024); } while (0)
; #define PG8_LDB(dst, b, h) do { _Pragma("unroll") for (int n = 0; n < 2; ++n) _Pragma("unroll") for (int k = 0; k < 2; ++k) dst[n][k] = *(const PG8_LAS bf16x8*)(lds + PG8_SB(b, h) + boff + n * 2048 + k * 1024); } while (0)
; #define PG8_MMA(ai, bj, At, Bt) do { __builtin_amdgcn_s_setprio(1); _Pragma("unroll") for (int m = 0; m < 4; ++m) _Pragma("unroll") for (int n = 0; n < 2; ++n) _Pragma("unroll") for (int k = 0; k < 2; ++k) \
;         acc[ai][bj][m][n] = __builtin_amdgcn_mfma_f32_16x16x32_bf16(Bt[n][k], At[m][k], acc[ai][bj][m][n], 0, 0, 0); __builtin_amdgcn_s_setprio(0); } while (0)
; #define PG8_BAR __builtin_amdgcn_s_barrier()
; template <class Epi, class Sched, bool ALIGN_EPI = false, bool SP2 = false>
; __device__ __forceinline__ void gemm_phase(PG8_LAS unsigned char* lds, const Gemm g, const Sched& S, const Epi& E) {
;     ...
;             if constexpr (SP2) {
;             PG8_LDB(B0, 0, 0); PG8_LDB(B1, 0, 1); PG8_SCHED; PG8_LDA(At, 0, 0); PG8_STAGE(PG8_SA(1, 1), a1 + hstep, voffA);
;             PG8_WAIT_V(8); PG8_WAIT_L(0); PG8_BAR; PG8_MMA(0, 0, At, B0); PG8_MMA(0, 1, At, B1); PG8_BAR; PG8_SCHED;
;             PG8_LDA(At, 0, 1); PG8_STAGE(PG8_SB(0, 0), b2, voffB); PG8_STAGE(PG8_SB(0, 1), b2 + hstep, voffB); PG8_STAGE(PG8_SA(0, 0), a2, voffA);
;             PG8_WAIT_V(8); PG8_WAIT_L(0); PG8_BAR; PG8_MMA(1, 0, At, B0); PG8_MMA(1, 1, At, B1); PG8_BAR; PG8_SCHED;
;             PG8_LDB(B0, 1, 0); PG8_LDB(B1, 1, 1); PG8_SCHED; PG8_LDA(At, 1, 0); PG8_STAGE(PG8_SA(0, 1), a2 + hstep, voffA);
;             PG8_WAIT_V(8); PG8_WAIT_L(0); PG8_BAR; PG8_MMA(0, 0, At, B0); PG8_MMA(0, 1, At, B1); PG8_BAR; PG8_SCHED;
;             PG8_LDA(At, 1, 1); PG8_STAGE(PG8_SB(1, 0), b3, voffB); PG8_STAGE(PG8_SB(1, 1), b3 + hstep, voffB); PG8_STAGE(PG8_SA(1, 0), a3, voffA);
;             PG8_WAIT_V(8); PG8_WAIT_L(0); PG8_BAR; PG8_MMA(1, 0, At, B0); PG8_MMA(1, 1, At, B1); PG8_BAR; PG8_SCHED;
	s_add_i32 s59, 0, 0x18000
	s_add_i32 s60, 0, 0x1c000
	v_add_u32_e32 v142, s59, v166
	v_add_u32_e32 v188, s60, v166
	ds_read_b128 v[130:133], v142
	ds_read_b128 v[134:137], v142 offset:1024
	ds_read_b128 v[138:141], v142 offset:2048
	ds_read_b128 v[142:145], v142 offset:3072
	ds_read_b128 v[162:165], v188
	ds_read_b128 v[180:183], v188 offset:1024
	ds_read_b128 v[184:187], v188 offset:2048
	ds_read_b128 v[188:191], v188 offset:3072
	ds_read_b128 v[196:199], v179 offset:32768
	ds_read_b128 v[200:203], v179 offset:33792
	ds_read_b128 v[204:207], v179 offset:34816
	ds_read_b128 v[208:211], v179 offset:35840
	ds_read_b128 v[212:215], v179 offset:36864
	ds_read_b128 v[220:223], v179 offset:37888
	ds_read_b128 v[224:227], v179 offset:38912
	ds_read_b128 v[228:231], v179 offset:39936
	s_add_u32 vcc_lo, s42, 0x100000
	s_addc_u32 vcc_hi, s43, 0
	s_add_i32 m0, s24, 0x4000
	s_nop 0
	global_load_lds_dwordx4 v146, vcc
	s_add_i32 m0, s24, 0x6000
	s_nop 0
	global_load_lds_dwordx4 v150, vcc
	s_waitcnt lgkmcnt(0)
	s_setprio 1
	v_mfma_f32_16x16x32_bf16 v[126:129], v[130:133], v[196:199], v[126:129]
	v_mfma_f32_16x16x32_bf16 v[126:129], v[134:137], v[200:203], v[126:129]
	v_mfma_f32_16x16x32_bf16 v[122:125], v[138:141], v[196:199], v[122:125]
	v_mfma_f32_16x16x32_bf16 v[122:125], v[142:145], v[200:203], v[122:125]
	v_mfma_f32_16x16x32_bf16 v[110:113], v[130:133], v[204:207], v[110:113]
	v_mfma_f32_16x16x32_bf16 v[110:113], v[134:137], v[208:211], v[110:113]
	v_mfma_f32_16x16x32_bf16 v[106:109], v[138:141], v[204:207], v[106:109]
	v_mfma_f32_16x16x32_bf16 v[106:109], v[142:145], v[208:211], v[106:109]
	v_mfma_f32_16x16x32_bf16 v[94:97], v[130:133], v[212:215], v[94:97]
	v_mfma_f32_16x16x32_bf16 v[94:97], v[134:137], v[220:223], v[94:97]
	v_mfma_f32_16x16x32_bf16 v[90:93], v[138:141], v[212:215], v[90:93]
	v_mfma_f32_16x16x32_bf16 v[90:93], v[142:145], v[220:223], v[90:93]
	v_mfma_f32_16x16x32_bf16 v[78:81], v[130:133], v[224:227], v[78:81]
	v_mfma_f32_16x16x32_bf16 v[78:81], v[134:137], v[228:231], v[78:81]
	v_mfma_f32_16x16x32_bf16 v[74:77], v[138:141], v[224:227], v[74:77]
	v_mfma_f32_16x16x32_bf16 v[74:77], v[142:145], v[228:231], v[74:77]
	v_mfma_f32_16x16x32_bf16 v[118:121], v[162:165], v[196:199], v[118:121]
	v_mfma_f32_16x16x32_bf16 v[118:121], v[180:183], v[200:203], v[118:121]
	v_mfma_f32_16x16x32_bf16 v[114:117], v[184:187], v[196:199], v[114:117]
	v_mfma_f32_16x16x32_bf16 v[114:117], v[188:191], v[200:203], v[114:117]
	v_mfma_f32_16x16x32_bf16 v[102:105], v[162:165], v[204:207], v[102:105]
	v_mfma_f32_16x16x32_bf16 v[102:105], v[180:183], v[208:211], v[102:105]
	v_mfma_f32_16x16x32_bf16 v[98:101], v[184:187], v[204:207], v[98:101]
	v_mfma_f32_16x16x32_bf16 v[98:101], v[188:191], v[208:211], v[98:101]
	v_mfma_f32_16x16x32_bf16 v[86:89], v[162:165], v[212:215], v[86:89]
	v_mfma_f32_16x16x32_bf16 v[86:89], v[180:183], v[220:223], v[86:89]
	v_mfma_f32_16x16x32_bf16 v[82:85], v[184:187], v[212:215], v[82:85]
	v_mfma_f32_16x16x32_bf16 v[82:85], v[188:191], v[220:223], v[82:85]
	v_mfma_f32_16x16x32_bf16 v[70:73], v[162:165], v[224:227], v[70:73]
	v_mfma_f32_16x16x32_bf16 v[70:73], v[180:183], v[228:231], v[70:73]
	v_mfma_f32_16x16x32_bf16 v[66:69], v[184:187], v[224:227], v[66:69]
	v_mfma_f32_16x16x32_bf16 v[66:69], v[188:191], v[228:231], v[66:69]
	s_setprio 0
	s_waitcnt vmcnt(8)
	s_barrier
	ds_read_b128 v[196:199], v179 offset:49152
	ds_read_b128 v[200:203], v179 offset:50176
	ds_read_b128 v[204:207], v179 offset:51200
	ds_read_b128 v[208:211], v179 offset:52224
	ds_read_b128 v[212:215], v179 offset:53248
	ds_read_b128 v[220:223], v179 offset:54272
	ds_read_b128 v[224:227], v179 offset:55296
	ds_read_b128 v[228:231], v179 offset:56320
	s_add_u32 s60, s40, 0x80
	s_addc_u32 s61, s41, 0
	s_add_u32 vcc_lo, s60, 0x100000
	s_addc_u32 vcc_hi, s61, 0
	s_add_i32 m0, s24, 0x18000
	s_nop 0
	global_load_lds_dwordx4 v148, s[60:61]
	s_add_i32 m0, s24, 0x1a000
	s_nop 0
	global_load_lds_dwordx4 v152, s[60:61]
	s_add_i32 m0, s24, 0x1c000
	s_nop 0
	global_load_lds_dwordx4 v148, vcc
	s_add_i32 m0, s24, 0x1e000
	s_nop 0
	global_load_lds_dwordx4 v152, vcc
	s_add_u32 s60, s42, 0x80
	s_addc_u32 s61, s43, 0
	s_add_i32 m0, s24, 0x8000
	s_nop 0
	global_load_lds_dwordx4 v146, s[60:61]
	s_add_i32 m0, s24, 0xa000
	s_nop 0
	global_load_lds_dwordx4 v150, s[60:61]
	s_waitcnt lgkmcnt(0)
	s_setprio 1
	v_mfma_f32_16x16x32_bf16 v[62:65], v[130:133], v[196:199], v[62:65]
	v_mfma_f32_16x16x32_bf16 v[62:65], v[134:137], v[200:203], v[62:65]
	v_mfma_f32_16x16x32_bf16 v[58:61], v[138:141], v[196:199], v[58:61]
	v_mfma_f32_16x16x32_bf16 v[58:61], v[142:145], v[200:203], v[58:61]
	v_mfma_f32_16x16x32_bf16 v[46:49], v[130:133], v[204:207], v[46:49]
	v_mfma_f32_16x16x32_bf16 v[46:49], v[134:137], v[208:211], v[46:49]
	v_mfma_f32_16x16x32_bf16 v[42:45], v[138:141], v[204:207], v[42:45]
	v_mfma_f32_16x16x32_bf16 v[42:45], v[142:145], v[208:211], v[42:45]
	v_mfma_f32_16x16x32_bf16 v[30:33], v[130:133], v[212:215], v[30:33]
	v_mfma_f32_16x16x32_bf16 v[30:33], v[134:137], v[220:223], v[30:33]
	v_mfma_f32_16x16x32_bf16 v[26:29], v[138:141], v[212:215], v[26:29]
	v_mfma_f32_16x16x32_bf16 v[26:29], v[142:145], v[220:223], v[26:29]
	v_mfma_f32_16x16x32_bf16 v[14:17], v[130:133], v[224:227], v[14:17]
	v_mfma_f32_16x16x32_bf16 v[14:17], v[134:137], v[228:231], v[14:17]
	v_mfma_f32_16x16x32_bf16 v[10:13], v[138:141], v[224:227], v[10:13]
	v_mfma_f32_16x16x32_bf16 v[10:13], v[142:145], v[228:231], v[10:13]
	v_mfma_f32_16x16x32_bf16 v[54:57], v[162:165], v[196:199], v[54:57]
	v_mfma_f32_16x16x32_bf16 v[54:57], v[180:183], v[200:203], v[54:57]
	v_mfma_f32_16x16x32_bf16 v[50:53], v[184:187], v[196:199], v[50:53]
	v_mfma_f32_16x16x32_bf16 v[50:53], v[188:191], v[200:203], v[50:53]
	v_mfma_f32_16x16x32_bf16 v[38:41], v[162:165], v[204:207], v[38:41]
	v_mfma_f32_16x16x32_bf16 v[38:41], v[180:183], v[208:211], v[38:41]
	v_mfma_f32_16x16x32_bf16 v[34:37], v[184:187], v[204:207], v[34:37]
	v_mfma_f32_16x16x32_bf16 v[34:37], v[188:191], v[208:211], v[34:37]
	v_mfma_f32_16x16x32_bf16 v[22:25], v[162:165], v[212:215], v[22:25]
	v_mfma_f32_16x16x32_bf16 v[22:25], v[180:183], v[220:223], v[22:25]
	v_mfma_f32_16x16x32_bf16 v[18:21], v[184:187], v[212:215], v[18:21]
	v_mfma_f32_16x16x32_bf16 v[18:21], v[188:191], v[220:223], v[18:21]
	v_mfma_f32_16x16x32_bf16 v[6:9], v[162:165], v[224:227], v[6:9]
	v_mfma_f32_16x16x32_bf16 v[6:9], v[180:183], v[228:231], v[6:9]
	v_mfma_f32_16x16x32_bf16 v[2:5], v[184:187], v[224:227], v[2:5]
	v_mfma_f32_16x16x32_bf16 v[2:5], v[188:191], v[228:231], v[2:5]
	s_setprio 0
	s_waitcnt vmcnt(8)
	s_barrier
	s_add_i32 s58, s58, 2
	s_add_u32 s36, s36, 0x100
	s_addc_u32 s37, s37, 0
	s_add_u32 s56, s56, 0x100
	s_addc_u32 s57, s57, 0
	s_cmp_gt_u32 s58, 61
	s_cbranch_scc0 .LBB0_1251
	s_branch .Lf1_exit
; #define PG8_STAGE(bufoff, gbase, voff) do { _Pragma("unroll") for (int _i = 0; _i < 2; ++_i) \
;         __builtin_amdgcn_global_load_lds((const unsigned*)((const char*)(gbase) + (voff)[_i]), (PG8_LAS unsigned*)(lds + (bufoff) + ldsw + _i * 8192), 16, 0, 0); } while (0)
; #define PG8_LDA(dst, b, h) do { _Pragma("unroll") for (int m = 0; m < 4; ++m) _Pragma("unroll") for (int k = 0; k < 2; ++k) dst[m][k] = *(const PG8_LAS bf16x8*)(lds + PG8_SA(b, h) + aoff + m * 2048 + k * 1024); } while (0)
; #define PG8_LDB(dst, b, h) do { _Pragma("unroll") for (int n = 0; n < 2; ++n) _Pragma("unroll") for (int k = 0; k < 2; ++k) dst[n][k] = *(const PG8_LAS bf16x8*)(lds + PG8_SB(b, h) + boff + n * 2048 + k * 1024); } while (0)
; #define PG8_MMA(ai, bj, At, Bt) do { __builtin_amdgcn_s_setprio(1); _Pragma("unroll") for (int m = 0; m < 4; ++m) _Pragma("unroll") for (int n = 0; n < 2; ++n) _Pragma("unroll") for (int k = 0; k < 2; ++k) \
;         acc[ai][bj][m][n] = __builtin_amdgcn_mfma_f32_16x16x32_bf16(Bt[n][k], At[m][k], acc[ai][bj][m][n], 0, 0, 0); __builtin_amdgcn_s_setprio(0); } while (0)
; #define PG8_BAR __builtin_amdgcn_s_barrier()
; template <class Epi, class Sched, bool ALIGN_EPI = false, bool SP2 = false>
; __device__ __forceinline__ void gemm_phase(PG8_LAS unsigned char* lds, const Gemm g, const Sched& S, const Epi& E) {
;     ...
;             if constexpr (SP2) {
;             PG8_LDB(B0, 0, 0); PG8_LDB(B1, 0, 1); PG8_SCHED; PG8_LDA(At, 0, 0); PG8_STAGE(PG8_SA(1, 1), a1 + hstep, voffA);
;             PG8_WAIT_V(8); PG8_WAIT_L(0); PG8_BAR; PG8_MMA(0, 0, At, B0); PG8_MMA(0, 1, At, B1); PG8_BAR; PG8_SCHED;
;             PG8_LDA(At, 0, 1); PG8_STAGE(PG8_SB(0, 0), b2, voffB); PG8_STAGE(PG8_SB(0, 1), b2 + hstep, voffB); PG8_STAGE(PG8_SA(0, 0), a2, voffA);
;             PG8_WAIT_V(8); PG8_WAIT_L(0); PG8_BAR; PG8_MMA(1, 0, At, B0); PG8_MMA(1, 1, At, B1); PG8_BAR; PG8_SCHED;
;             PG8_LDB(B0, 1, 0); PG8_LDB(B1, 1, 1); PG8_SCHED; PG8_LDA(At, 1, 0); PG8_STAGE(PG8_SA(0, 1), a2 + hstep, voffA);
;             PG8_WAIT_V(8); PG8_WAIT_L(0); PG8_BAR; PG8_MMA(0, 0, At, B0); PG8_MMA(0, 1, At, B1); PG8_BAR; PG8_SCHED;
;             PG8_LDA(At, 1, 1); PG8_STAGE(PG8_SB(1, 0), b3, voffB); PG8_STAGE(PG8_SB(1, 1), b3 + hstep, voffB); PG8_STAGE(PG8_SA(1, 0), a3, voffA);
;             PG8_WAIT_V(8); PG8_WAIT_L(0); PG8_BAR; PG8_MMA(1, 0, At, B0); PG8_MMA(1, 1, At, B1); PG8_BAR; PG8_SCHED;
.Lf1_h1:
	ds_read_b128 v[130:133], v177
	ds_read_b128 v[134:137], v177 offset:1024
	ds_read_b128 v[138:141], v177 offset:2048
	ds_read_b128 v[142:145], v177 offset:3072
	ds_read_b128 v[162:165], v178
	ds_read_b128 v[180:183], v178 offset:1024
	ds_read_b128 v[184:187], v178 offset:2048
	ds_read_b128 v[188:191], v178 offset:3072
	s_add_u32 s40, s36, 0xfff00080
	s_addc_u32 s41, s37, -1
	s_cmp_eq_u32 s58, 60
	s_cselect_b32 s43, s15, s41
	s_cselect_b32 s42, s17, s40
	s_cselect_b32 s41, s54, s57
	s_cselect_b32 s40, s55, s56
	ds_read_b128 v[196:199], v179
	ds_read_b128 v[200:203], v179 offset:1024
	ds_read_b128 v[204:207], v179 offset:2048
	ds_read_b128 v[208:211], v179 offset:3072
	ds_read_b128 v[212:215], v179 offset:4096
	ds_read_b128 v[220:223], v179 offset:5120
	ds_read_b128 v[224:227], v179 offset:6144
	ds_read_b128 v[228:231], v179 offset:7168
	s_add_i32 m0, s24, 0xc000
	s_nop 0
	global_load_lds_dwordx4 v146, s[36:37]
	s_add_i32 m0, s24, 0xe000
	s_nop 0
	global_load_lds_dwordx4 v150, s[36:37]
	s_sleep 2
	s_waitcnt lgkmcnt(0)
	s_waitcnt vmcnt(8)
	s_barrier
	s_setprio 2
	v_mfma_f32_16x16x32_bf16 v[126:129], v[130:133], v[196:199], v[126:129]
	v_mfma_f32_16x16x32_bf16 v[126:129], v[134:137], v[200:203], v[126:129]
	v_mfma_f32_16x16x32_bf16 v[122:125], v[138:141], v[196:199], v[122:125]
	v_mfma_f32_16x16x32_bf16 v[122:125], v[142:145], v[200:203], v[122:125]
	v_mfma_f32_16x16x32_bf16 v[110:113], v[130:133], v[204:207], v[110:113]
	v_mfma_f32_16x16x32_bf16 v[110:113], v[134:137], v[208:211], v[110:113]
	v_mfma_f32_16x16x32_bf16 v[106:109], v[138:141], v[204:207], v[106:109]
	v_mfma_f32_16x16x32_bf16 v[106:109], v[142:145], v[208:211], v[106:109]
	v_mfma_f32_16x16x32_bf16 v[94:97], v[130:133], v[212:215], v[94:97]
	v_mfma_f32_16x16x32_bf16 v[94:97], v[134:137], v[220:223], v[94:97]
	v_mfma_f32_16x16x32_bf16 v[90:93], v[138:141], v[212:215], v[90:93]
	v_mfma_f32_16x16x32_bf16 v[90:93], v[142:145], v[220:223], v[90:93]
	v_mfma_f32_16x16x32_bf16 v[78:81], v[130:133], v[224:227], v[78:81]
	v_mfma_f32_16x16x32_bf16 v[78:81], v[134:137], v[228:231], v[78:81]
	v_mfma_f32_16x16x32_bf16 v[74:77], v[138:141], v[224:227], v[74:77]
	v_mfma_f32_16x16x32_bf16 v[74:77], v[142:145], v[228:231], v[74:77]
	v_mfma_f32_16x16x32_bf16 v[118:121], v[162:165], v[196:199], v[118:121]
	v_mfma_f32_16x16x32_bf16 v[118:121], v[180:183], v[200:203], v[118:121]
	v_mfma_f32_16x16x32_bf16 v[114:117], v[184:187], v[196:199], v[114:117]
	v_mfma_f32_16x16x32_bf16 v[114:117], v[188:191], v[200:203], v[114:117]
	v_mfma_f32_16x16x32_bf16 v[102:105], v[162:165], v[204:207], v[102:105]
	v_mfma_f32_16x16x32_bf16 v[102:105], v[180:183], v[208:211], v[102:105]
	v_mfma_f32_16x16x32_bf16 v[98:101], v[184:187], v[204:207], v[98:101]
	v_mfma_f32_16x16x32_bf16 v[98:101], v[188:191], v[208:211], v[98:101]
	v_mfma_f32_16x16x32_bf16 v[86:89], v[162:165], v[212:215], v[86:89]
	v_mfma_f32_16x16x32_bf16 v[86:89], v[180:183], v[220:223], v[86:89]
	v_mfma_f32_16x16x32_bf16 v[82:85], v[184:187], v[212:215], v[82:85]
	v_mfma_f32_16x16x32_bf16 v[82:85], v[188:191], v[220:223], v[82:85]
	v_mfma_f32_16x16x32_bf16 v[70:73], v[162:165], v[224:227], v[70:73]
	v_mfma_f32_16x16x32_bf16 v[70:73], v[180:183], v[228:231], v[70:73]
	v_mfma_f32_16x16x32_bf16 v[66:69], v[184:187], v[224:227], v[66:69]
	v_mfma_f32_16x16x32_bf16 v[66:69], v[188:191], v[228:231], v[66:69]
	s_setprio 0
	ds_read_b128 v[196:199], v179 offset:16384
	ds_read_b128 v[200:203], v179 offset:17408
	ds_read_b128 v[204:207], v179 offset:18432
	ds_read_b128 v[208:211], v179 offset:19456
	ds_read_b128 v[212:215], v179 offset:20480
	ds_read_b128 v[220:223], v179 offset:21504
	ds_read_b128 v[224:227], v179 offset:22528
	ds_read_b128 v[228:231], v179 offset:23552
	s_add_u32 vcc_lo, s40, 0x100000
	s_addc_u32 vcc_hi, s41, 0
	s_add_i32 m0, s24, 0x10000
	s_nop 0
	global_load_lds_dwordx4 v148, s[40:41]
	s_add_i32 m0, s24, 0x12000
	s_nop 0
	global_load_lds_dwordx4 v152, s[40:41]
	s_add_i32 m0, s24, 0x14000
	s_nop 0
	global_load_lds_dwordx4 v148, vcc
	s_add_i32 m0, s24, 0x16000
	s_nop 0
	global_load_lds_dwordx4 v152, vcc
	s_mov_b32 m0, s24
	s_nop 0
	global_load_lds_dwordx4 v146, s[42:43]
	s_add_i32 m0, s24, 0x2000
	s_nop 0
	global_load_lds_dwordx4 v150, s[42:43]
	s_sleep 2
	s_waitcnt lgkmcnt(0)
	s_waitcnt vmcnt(8)
	s_barrier
; #define PG8_STAGE(bufoff, gbase, voff) do { _Pragma("unroll") for (int _i = 0; _i < 2; ++_i) \
;         __builtin_amdgcn_global_load_lds((const unsigned*)((const char*)(gbase) + (voff)[_i]), (PG8_LAS unsigned*)(lds + (bufoff) + ldsw + _i * 8192), 16, 0, 0); } while (0)
; #define PG8_LDA(dst, b, h) do { _Pragma("unroll") for (int m = 0; m < 4; ++m) _Pragma("unroll") for (int k = 0; k < 2; ++k) dst[m][k] = *(const PG8_LAS bf16x8*)(lds + PG8_SA(b, h) + aoff + m * 2048 + k * 1024); } while (0)
; #define PG8_LDB(dst, b, h) do { _Pragma("unroll") for (int n = 0; n < 2; ++n) _Pragma("unroll") for (int k = 0; k < 2; ++k) dst[n][k] = *(const PG8_LAS bf16x8*)(lds + PG8_SB(b, h) + boff + n * 2048 + k * 1024); } while (0)
; #define PG8_MMA(ai, bj, At, Bt) do { __builtin_amdgcn_s_setprio(1); _Pragma("unroll") for (int m = 0; m < 4; ++m) _Pragma("unroll") for (int n = 0; n < 2; ++n) _Pragma("unroll") for (int k = 0; k < 2; ++k) \
;         acc[ai][bj][m][n] = __builtin_amdgcn_mfma_f32_16x16x32_bf16(Bt[n][k], At[m][k], acc[ai][bj][m][n], 0, 0, 0); __builtin_amdgcn_s_setprio(0); } while (0)
; #define PG8_BAR __builtin_amdgcn_s_barrier()
; template <class Epi, class Sched, bool ALIGN_EPI = false, bool SP2 = false>
; __device__ __forceinline__ void gemm_phase(PG8_LAS unsigned char* lds, const Gemm g, const Sched& S, const Epi& E) {
;     ...
;             if constexpr (SP2) {
;             PG8_LDB(B0, 0, 0); PG8_LDB(B1, 0, 1); PG8_SCHED; PG8_LDA(At, 0, 0); PG8_STAGE(PG8_SA(1, 1), a1 + hstep, voffA);
;             PG8_WAIT_V(8); PG8_WAIT_L(0); PG8_BAR; PG8_MMA(0, 0, At, B0); PG8_MMA(0, 1, At, B1); PG8_BAR; PG8_SCHED;
;             PG8_LDA(At, 0, 1); PG8_STAGE(PG8_SB(0, 0), b2, voffB); PG8_STAGE(PG8_SB(0, 1), b2 + hstep, voffB); PG8_STAGE(PG8_SA(0, 0), a2, voffA);
;             PG8_WAIT_V(8); PG8_WAIT_L(0); PG8_BAR; PG8_MMA(1, 0, At, B0); PG8_MMA(1, 1, At, B1); PG8_BAR; PG8_SCHED;
;             PG8_LDB(B0, 1, 0); PG8_LDB(B1, 1, 1); PG8_SCHED; PG8_LDA(At, 1, 0); PG8_STAGE(PG8_SA(0, 1), a2 + hstep, voffA);
;             PG8_WAIT_V(8); PG8_WAIT_L(0); PG8_BAR; PG8_MMA(0, 0, At, B0); PG8_MMA(0, 1, At, B1); PG8_BAR; PG8_SCHED;
;             PG8_LDA(At, 1, 1); PG8_STAGE(PG8_SB(1, 0), b3, voffB); PG8_STAGE(PG8_SB(1, 1), b3 + hstep, voffB); PG8_STAGE(PG8_SA(1, 0), a3, voffA);
;             PG8_WAIT_V(8); PG8_WAIT_L(0); PG8_BAR; PG8_MMA(1, 0, At, B0); PG8_MMA(1, 1, At, B1); PG8_BAR; PG8_SCHED;
	s_setprio 2
	v_mfma_f32_16x16x32_bf16 v[62:65], v[130:133], v[196:199], v[62:65]
	v_mfma_f32_16x16x32_bf16 v[62:65], v[134:137], v[200:203], v[62:65]
	v_mfma_f32_16x16x32_bf16 v[58:61], v[138:141], v[196:199], v[58:61]
	v_mfma_f32_16x16x32_bf16 v[58:61], v[142:145], v[200:203], v[58:61]
	v_mfma_f32_16x16x32_bf16 v[46:49], v[130:133], v[204:207], v[46:49]
	v_mfma_f32_16x16x32_bf16 v[46:49], v[134:137], v[208:211], v[46:49]
	v_mfma_f32_16x16x32_bf16 v[42:45], v[138:141], v[204:207], v[42:45]
	v_mfma_f32_16x16x32_bf16 v[42:45], v[142:145], v[208:211], v[42:45]
	v_mfma_f32_16x16x32_bf16 v[30:33], v[130:133], v[212:215], v[30:33]
	v_mfma_f32_16x16x32_bf16 v[30:33], v[134:137], v[220:223], v[30:33]
	v_mfma_f32_16x16x32_bf16 v[26:29], v[138:141], v[212:215], v[26:29]
	v_mfma_f32_16x16x32_bf16 v[26:29], v[142:145], v[220:223], v[26:29]
	v_mfma_f32_16x16x32_bf16 v[14:17], v[130:133], v[224:227], v[14:17]
	v_mfma_f32_16x16x32_bf16 v[14:17], v[134:137], v[228:231], v[14:17]
	v_mfma_f32_16x16x32_bf16 v[10:13], v[138:141], v[224:227], v[10:13]
	v_mfma_f32_16x16x32_bf16 v[10:13], v[142:145], v[228:231], v[10:13]
	v_mfma_f32_16x16x32_bf16 v[54:57], v[162:165], v[196:199], v[54:57]
	v_mfma_f32_16x16x32_bf16 v[54:57], v[180:183], v[200:203], v[54:57]
	v_mfma_f32_16x16x32_bf16 v[50:53], v[184:187], v[196:199], v[50:53]
	v_mfma_f32_16x16x32_bf16 v[50:53], v[188:191], v[200:203], v[50:53]
	v_mfma_f32_16x16x32_bf16 v[38:41], v[162:165], v[204:207], v[38:41]
	v_mfma_f32_16x16x32_bf16 v[38:41], v[180:183], v[208:211], v[38:41]
	v_mfma_f32_16x16x32_bf16 v[34:37], v[184:187], v[204:207], v[34:37]
	v_mfma_f32_16x16x32_bf16 v[34:37], v[188:191], v[208:211], v[34:37]
	v_mfma_f32_16x16x32_bf16 v[22:25], v[162:165], v[212:215], v[22:25]
	v_mfma_f32_16x16x32_bf16 v[22:25], v[180:183], v[220:223], v[22:25]
	v_mfma_f32_16x16x32_bf16 v[18:21], v[184:187], v[212:215], v[18:21]
	v_mfma_f32_16x16x32_bf16 v[18:21], v[188:191], v[220:223], v[18:21]
	v_mfma_f32_16x16x32_bf16 v[6:9], v[162:165], v[224:227], v[6:9]
	v_mfma_f32_16x16x32_bf16 v[6:9], v[180:183], v[228:231], v[6:9]
	v_mfma_f32_16x16x32_bf16 v[2:5], v[184:187], v[224:227], v[2:5]
	v_mfma_f32_16x16x32_bf16 v[2:5], v[188:191], v[228:231], v[2:5]
	s_setprio 0
	s_add_i32 s59, 0, 0x18000
	s_add_i32 s60, 0, 0x1c000
	v_add_u32_e32 v142, s59, v166
	v_add_u32_e32 v188, s60, v166
	ds_read_b128 v[130:133], v142
	ds_read_b128 v[134:137], v142 offset:1024
	ds_read_b128 v[138:141], v142 offset:2048
	ds_read_b128 v[142:145], v142 offset:3072
	ds_read_b128 v[162:165], v188
	ds_read_b128 v[180:183], v188 offset:1024
	ds_read_b128 v[184:187], v188 offset:2048
	ds_read_b128 v[188:191], v188 offset:3072
	ds_read_b128 v[196:199], v179 offset:32768
	ds_read_b128 v[200:203], v179 offset:33792
	ds_read_b128 v[204:207], v179 offset:34816
	ds_read_b128 v[208:211], v179 offset:35840
	ds_read_b128 v[212:215], v179 offset:36864
	ds_read_b128 v[220:223], v179 offset:37888
	ds_read_b128 v[224:227], v179 offset:38912
	ds_read_b128 v[228:231], v179 offset:39936
	s_add_u32 vcc_lo, s42, 0x100000
	s_addc_u32 vcc_hi, s43, 0
	s_add_i32 m0, s24, 0x4000
	s_nop 0
	global_load_lds_dwordx4 v146, vcc
	s_add_i32 m0, s24, 0x6000
	s_nop 0
	global_load_lds_dwordx4 v150, vcc
	s_sleep 2
	s_waitcnt lgkmcnt(0)
	s_waitcnt vmcnt(8)
	s_barrier
; #define PG8_STAGE(bufoff, gbase, voff) do { _Pragma("unroll") for (int _i = 0; _i < 2; ++_i) \
;         __builtin_amdgcn_global_load_lds((const unsigned*)((const char*)(gbase) + (voff)[_i]), (PG8_LAS unsigned*)(lds + (bufoff) + ldsw + _i * 8192), 16, 0, 0); } while (0)
; #define PG8_LDA(dst, b, h) do { _Pragma("unroll") for (int m = 0; m < 4; ++m) _Pragma("unroll") for (int k = 0; k < 2; ++k) dst[m][k] = *(const PG8_LAS bf16x8*)(lds + PG8_SA(b, h) + aoff + m * 2048 + k * 1024); } while (0)
; #define PG8_LDB(dst, b, h) do { _Pragma("unroll") for (int n = 0; n < 2; ++n) _Pragma("unroll") for (int k = 0; k < 2; ++k) dst[n][k] = *(const PG8_LAS bf16x8*)(lds + PG8_SB(b, h) + boff + n * 2048 + k * 1024); } while (0)
; #define PG8_MMA(ai, bj, At, Bt) do { __builtin_amdgcn_s_setprio(1); _Pragma("unroll") for (int m = 0; m < 4; ++m) _Pragma("unroll") for (int n = 0; n < 2; ++n) _Pragma("unroll") for (int k = 0; k < 2; ++k) \
;         acc[ai][bj][m][n] = __builtin_amdgcn_mfma_f32_16x16x32_bf16(Bt[n][k], At[m][k], acc[ai][bj][m][n], 0, 0, 0); __builtin_amdgcn_s_setprio(0); } while (0)
; #define PG8_WAIT_V(n) asm volatile("s_waitcnt vmcnt(" #n ")" ::: "memory")
; #define PG8_WAIT_L(n) asm volatile("s_waitcnt lgkmcnt(" #n ")" ::: "memory")
; #define PG8_BAR __builtin_amdgcn_s_barrier()
; #define PG8_SCHED __builtin_amdgcn_sched_barrier(0)
; template <class Epi, class Sched, bool ALIGN_EPI = false, bool SP2 = false>
; __device__ __forceinline__ void gemm_phase(PG8_LAS unsigned char* lds, const Gemm g, const Sched& S, const Epi& E) {
;     ...
;             PG8_LDB(B0, 1, 0); PG8_LDB(B1, 1, 1); PG8_SCHED; PG8_LDA(At, 1, 0); PG8_STAGE(PG8_SA(0, 1), a2 + hstep, voffA);
;             PG8_WAIT_V(8); PG8_WAIT_L(0); PG8_BAR; PG8_MMA(0, 0, At, B0); PG8_MMA(0, 1, At, B1); PG8_BAR; PG8_SCHED;
;             PG8_LDA(At, 1, 1); PG8_STAGE(PG8_SB(1, 0), b3, voffB); PG8_STAGE(PG8_SB(1, 1), b3 + hstep, voffB); PG8_STAGE(PG8_SA(1, 0), a3, voffA);
;             PG8_WAIT_V(8); PG8_WAIT_L(0); PG8_BAR; PG8_MMA(1, 0, At, B0); PG8_MMA(1, 1, At, B1); PG8_BAR; PG8_SCHED;
	s_setprio 2
	v_mfma_f32_16x16x32_bf16 v[126:129], v[130:133], v[196:199], v[126:129]
	v_mfma_f32_16x16x32_bf16 v[126:129], v[134:137], v[200:203], v[126:129]
	v_mfma_f32_16x16x32_bf16 v[122:125], v[138:141], v[196:199], v[122:125]
	v_mfma_f32_16x16x32_bf16 v[122:125], v[142:145], v[200:203], v[122:125]
	v_mfma_f32_16x16x32_bf16 v[110:113], v[130:133], v[204:207], v[110:113]
	v_mfma_f32_16x16x32_bf16 v[110:113], v[134:137], v[208:211], v[110:113]
	v_mfma_f32_16x16x32_bf16 v[106:109], v[138:141], v[204:207], v[106:109]
	v_mfma_f32_16x16x32_bf16 v[106:109], v[142:145], v[208:211], v[106:109]
	v_mfma_f32_16x16x32_bf16 v[94:97], v[130:133], v[212:215], v[94:97]
	v_mfma_f32_16x16x32_bf16 v[94:97], v[134:137], v[220:223], v[94:97]
	v_mfma_f32_16x16x32_bf16 v[90:93], v[138:141], v[212:215], v[90:93]
	v_mfma_f32_16x16x32_bf16 v[90:93], v[142:145], v[220:223], v[90:93]
	v_mfma_f32_16x16x32_bf16 v[78:81], v[130:133], v[224:227], v[78:81]
	v_mfma_f32_16x16x32_bf16 v[78:81], v[134:137], v[228:231], v[78:81]
	v_mfma_f32_16x16x32_bf16 v[74:77], v[138:141], v[224:227], v[74:77]
	v_mfma_f32_16x16x32_bf16 v[74:77], v[142:145], v[228:231], v[74:77]
	v_mfma_f32_16x16x32_bf16 v[118:121], v[162:165], v[196:199], v[118:121]
	v_mfma_f32_16x16x32_bf16 v[118:121], v[180:183], v[200:203], v[118:121]
	v_mfma_f32_16x16x32_bf16 v[114:117], v[184:187], v[196:199], v[114:117]
	v_mfma_f32_16x16x32_bf16 v[114:117], v[188:191], v[200:203], v[114:117]
	v_mfma_f32_16x16x32_bf16 v[102:105], v[162:165], v[204:207], v[102:105]
	v_mfma_f32_16x16x32_bf16 v[102:105], v[180:183], v[208:211], v[102:105]
	v_mfma_f32_16x16x32_bf16 v[98:101], v[184:187], v[204:207], v[98:101]
	v_mfma_f32_16x16x32_bf16 v[98:101], v[188:191], v[208:211], v[98:101]
	v_mfma_f32_16x16x32_bf16 v[86:89], v[162:165], v[212:215], v[86:89]
	v_mfma_f32_16x16x32_bf16 v[86:89], v[180:183], v[220:223], v[86:89]
	v_mfma_f32_16x16x32_bf16 v[82:85], v[184:187], v[212:215], v[82:85]
	v_mfma_f32_16x16x32_bf16 v[82:85], v[188:191], v[220:223], v[82:85]
	v_mfma_f32_16x16x32_bf16 v[70:73], v[162:165], v[224:227], v[70:73]
	v_mfma_f32_16x16x32_bf16 v[70:73], v[180:183], v[228:231], v[70:73]
	v_mfma_f32_16x16x32_bf16 v[66:69], v[184:187], v[224:227], v[66:69]
	v_mfma_f32_16x16x32_bf16 v[66:69], v[188:191], v[228:231], v[66:69]
	s_setprio 0
	ds_read_b128 v[196:199], v179 offset:49152
	ds_read_b128 v[200:203], v179 offset:50176
	ds_read_b128 v[204:207], v179 offset:51200
	ds_read_b128 v[208:211], v179 offset:52224
	ds_read_b128 v[212:215], v179 offset:53248
	ds_read_b128 v[220:223], v179 offset:54272
	ds_read_b128 v[224:227], v179 offset:55296
	ds_read_b128 v[228:231], v179 offset:56320
	s_add_u32 s60, s40, 0x80
	s_addc_u32 s61, s41, 0
	s_add_u32 vcc_lo, s60, 0x100000
	s_addc_u32 vcc_hi, s61, 0
	s_add_i32 m0, s24, 0x18000
	s_nop 0
	global_load_lds_dwordx4 v148, s[60:61]
	s_add_i32 m0, s24, 0x1a000
	s_nop 0
	global_load_lds_dwordx4 v152, s[60:61]
	s_add_i32 m0, s24, 0x1c000
	s_nop 0
	global_load_lds_dwordx4 v148, vcc
	s_add_i32 m0, s24, 0x1e000
	s_nop 0
	global_load_lds_dwordx4 v152, vcc
	s_add_u32 s60, s42, 0x80
	s_addc_u32 s61, s43, 0
	s_add_i32 m0, s24, 0x8000
	s_nop 0
	global_load_lds_dwordx4 v146, s[60:61]
	s_add_i32 m0, s24, 0xa000
	s_nop 0
	global_load_lds_dwordx4 v150, s[60:61]
	s_sleep 2
	s_waitcnt lgkmcnt(0)
	s_waitcnt vmcnt(8)
	s_barrier
	s_setprio 2
	v_mfma_f32_16x16x32_bf16 v[62:65], v[130:133], v[196:199], v[62:65]
	v_mfma_f32_16x16x32_bf16 v[62:65], v[134:137], v[200:203], v[62:65]
	v_mfma_f32_16x16x32_bf16 v[58:61], v[138:141], v[196:199], v[58:61]
	v_mfma_f32_16x16x32_bf16 v[58:61], v[142:145], v[200:203], v[58:61]
	v_mfma_f32_16x16x32_bf16 v[46:49], v[130:133], v[204:207], v[46:49]
	v_mfma_f32_16x16x32_bf16 v[46:49], v[134:137], v[208:211], v[46:49]
	v_mfma_f32_16x16x32_bf16 v[42:45], v[138:141], v[204:207], v[42:45]
	v_mfma_f32_16x16x32_bf16 v[42:45], v[142:145], v[208:211], v[42:45]
	v_mfma_f32_16x16x32_bf16 v[30:33], v[130:133], v[212:215], v[30:33]
	v_mfma_f32_16x16x32_bf16 v[30:33], v[134:137], v[220:223], v[30:33]
	v_mfma_f32_16x16x32_bf16 v[26:29], v[138:141], v[212:215], v[26:29]
	v_mfma_f32_16x16x32_bf16 v[26:29], v[142:145], v[220:223], v[26:29]
	v_mfma_f32_16x16x32_bf16 v[14:17], v[130:133], v[224:227], v[14:17]
	v_mfma_f32_16x16x32_bf16 v[14:17], v[134:137], v[228:231], v[14:17]
	v_mfma_f32_16x16x32_bf16 v[10:13], v[138:141], v[224:227], v[10:13]
	v_mfma_f32_16x16x32_bf16 v[10:13], v[142:145], v[228:231], v[10:13]
	v_mfma_f32_16x16x32_bf16 v[54:57], v[162:165], v[196:199], v[54:57]
	v_mfma_f32_16x16x32_bf16 v[54:57], v[180:183], v[200:203], v[54:57]
	v_mfma_f32_16x16x32_bf16 v[50:53], v[184:187], v[196:199], v[50:53]
	v_mfma_f32_16x16x32_bf16 v[50:53], v[188:191], v[200:203], v[50:53]
	v_mfma_f32_16x16x32_bf16 v[38:41], v[162:165], v[204:207], v[38:41]
	v_mfma_f32_16x16x32_bf16 v[38:41], v[180:183], v[208:211], v[38:41]
	v_mfma_f32_16x16x32_bf16 v[34:37], v[184:187], v[204:207], v[34:37]
	v_mfma_f32_16x16x32_bf16 v[34:37], v[188:191], v[208:211], v[34:37]
	v_mfma_f32_16x16x32_bf16 v[22:25], v[162:165], v[212:215], v[22:25]
	v_mfma_f32_16x16x32_bf16 v[22:25], v[180:183], v[220:223], v[22:25]
	v_mfma_f32_16x16x32_bf16 v[18:21], v[184:187], v[212:215], v[18:21]
	v_mfma_f32_16x16x32_bf16 v[18:21], v[188:191], v[220:223], v[18:21]
	v_mfma_f32_16x16x32_bf16 v[6:9], v[162:165], v[224:227], v[6:9]
	v_mfma_f32_16x16x32_bf16 v[6:9], v[180:183], v[228:231], v[6:9]
	v_mfma_f32_16x16x32_bf16 v[2:5], v[184:187], v[224:227], v[2:5]
	v_mfma_f32_16x16x32_bf16 v[2:5], v[188:191], v[228:231], v[2:5]
	s_setprio 0
	s_add_i32 s58, s58, 2
	s_add_u32 s36, s36, 0x100
	s_addc_u32 s37, s37, 0
	s_add_u32 s56, s56, 0x100
	s_addc_u32 s57, s57, 0
	s_cmp_gt_u32 s58, 61
	s_cbranch_scc0 .Lf1_h1

; #define PG8_STAGE(bufoff, gbase, voff) do { _Pragma("unroll") for (int _i = 0; _i < 2; ++_i) \
;         __builtin_amdgcn_global_load_lds((const unsigned*)((const char*)(gbase) + (voff)[_i]), (PG8_LAS unsigned*)(lds + (bufoff) + ldsw + _i * 8192), 16, 0, 0); } while (0)
; #define PG8_LDA(dst, b, h) do { _Pragma("unroll") for (int m = 0; m < 4; ++m) _Pragma("unroll") for (int k = 0; k < 2; ++k) dst[m][k] = *(const PG8_LAS bf16x8*)(lds + PG8_SA(b, h) + aoff + m * 2048 + k * 1024); } while (0)
; #define PG8_LDB(dst, b, h) do { _Pragma("unroll") for (int n = 0; n < 2; ++n) _Pragma("unroll") for (int k = 0; k < 2; ++k) dst[n][k] = *(const PG8_LAS bf16x8*)(lds + PG8_SB(b, h) + boff + n * 2048 + k * 1024); } while (0)
; #define PG8_MMA(ai, bj, At, Bt) do { __builtin_amdgcn_s_setprio(1); _Pragma("unroll") for (int m = 0; m < 4; ++m) _Pragma("unroll") for (int n = 0; n < 2; ++n) _Pragma("unroll") for (int k = 0; k < 2; ++k) \
;         acc[ai][bj][m][n] = __builtin_amdgcn_mfma_f32_16x16x32_bf16(Bt[n][k], At[m][k], acc[ai][bj][m][n], 0, 0, 0); __builtin_amdgcn_s_setprio(0); } while (0)
; #define PG8_WAIT_V(n) asm volatile("s_waitcnt vmcnt(" #n ")" ::: "memory")
; #define PG8_WAIT_L(n) asm volatile("s_waitcnt lgkmcnt(" #n ")" ::: "memory")
; #define PG8_BAR __builtin_amdgcn_s_barrier()
; #define PG8_SCHED __builtin_amdgcn_sched_barrier(0)
; template <class Epi, class Sched, bool ALIGN_EPI = false, bool SP2 = false>
; __device__ __forceinline__ void gemm_phase(PG8_LAS unsigned char* lds, const Gemm g, const Sched& S, const Epi& E) {
;     ...
;             if constexpr (SP2) {
;             PG8_LDB(B0, 0, 0); PG8_LDB(B1, 0, 1); PG8_SCHED; PG8_LDA(At, 0, 0); PG8_STAGE(PG8_SA(1, 1), a1 + hstep, voffA);
;             PG8_WAIT_V(8); PG8_WAIT_L(0); PG8_BAR; PG8_MMA(0, 0, At, B0); PG8_MMA(0, 1, At, B1); PG8_BAR; PG8_SCHED;
;             PG8_LDA(At, 0, 1); PG8_STAGE(PG8_SB(0, 0), b2, voffB); PG8_STAGE(PG8_SB(0, 1), b2 + hstep, voffB); PG8_STAGE(PG8_SA(0, 0), a2, voffA);
;             PG8_WAIT_V(8); PG8_WAIT_L(0); PG8_BAR; PG8_MMA(1, 0, At, B0); PG8_MMA(1, 1, At, B1); PG8_BAR; PG8_SCHED;
.LBB0_1321:
	ds_read_b128 v[128:131], v156
	ds_read_b128 v[132:135], v156 offset:1024
	ds_read_b128 v[150:153], v156 offset:2048
	ds_read_b128 v[162:165], v156 offset:3072
	ds_read_b128 v[166:169], v157
	ds_read_b128 v[170:173], v157 offset:1024
	ds_read_b128 v[174:177], v157 offset:2048
	ds_read_b128 v[178:181], v157 offset:3072
	s_add_u32 s20, s18, 0xffbfc080
	s_addc_u32 s21, s19, -1
	s_cmpk_eq_i32 s59, 0xfc
	s_cselect_b32 s23, s7, s21
	s_cselect_b32 s22, s6, s20
	s_cselect_b32 s21, s17, s58
	s_cselect_b32 s20, s16, s57
	ds_read_b128 v[182:185], v158
	ds_read_b128 v[186:189], v158 offset:1024
	ds_read_b128 v[190:193], v158 offset:2048
	ds_read_b128 v[194:197], v158 offset:3072
	ds_read_b128 v[198:201], v158 offset:4096
	ds_read_b128 v[202:205], v158 offset:5120
	ds_read_b128 v[206:209], v158 offset:6144
	ds_read_b128 v[210:213], v158 offset:7168
	s_add_i32 m0, s24, 0xc000
	s_nop 0
	global_load_lds_dwordx4 v136, s[18:19]
	s_add_i32 m0, s24, 0xe000
	s_nop 0
	global_load_lds_dwordx4 v140, s[18:19]
	s_waitcnt lgkmcnt(0)
	s_setprio 1
	v_mfma_f32_16x16x32_bf16 v[124:127], v[128:131], v[182:185], v[124:127]
	v_mfma_f32_16x16x32_bf16 v[124:127], v[132:135], v[186:189], v[124:127]
	v_mfma_f32_16x16x32_bf16 v[120:123], v[150:153], v[182:185], v[120:123]
	v_mfma_f32_16x16x32_bf16 v[120:123], v[162:165], v[186:189], v[120:123]
	v_mfma_f32_16x16x32_bf16 v[116:119], v[128:131], v[190:193], v[116:119]
	v_mfma_f32_16x16x32_bf16 v[116:119], v[132:135], v[194:197], v[116:119]
	v_mfma_f32_16x16x32_bf16 v[112:115], v[150:153], v[190:193], v[112:115]
	v_mfma_f32_16x16x32_bf16 v[112:115], v[162:165], v[194:197], v[112:115]
	v_mfma_f32_16x16x32_bf16 v[108:111], v[128:131], v[198:201], v[108:111]
	v_mfma_f32_16x16x32_bf16 v[108:111], v[132:135], v[202:205], v[108:111]
	v_mfma_f32_16x16x32_bf16 v[104:107], v[150:153], v[198:201], v[104:107]
	v_mfma_f32_16x16x32_bf16 v[104:107], v[162:165], v[202:205], v[104:107]
	v_mfma_f32_16x16x32_bf16 v[100:103], v[128:131], v[206:209], v[100:103]
	v_mfma_f32_16x16x32_bf16 v[100:103], v[132:135], v[210:213], v[100:103]
	v_mfma_f32_16x16x32_bf16 v[96:99], v[150:153], v[206:209], v[96:99]
	v_mfma_f32_16x16x32_bf16 v[96:99], v[162:165], v[210:213], v[96:99]
	v_mfma_f32_16x16x32_bf16 v[68:71], v[166:169], v[182:185], v[68:71]
	v_mfma_f32_16x16x32_bf16 v[68:71], v[170:173], v[186:189], v[68:71]
	v_mfma_f32_16x16x32_bf16 v[64:67], v[174:177], v[182:185], v[64:67]
	v_mfma_f32_16x16x32_bf16 v[64:67], v[178:181], v[186:189], v[64:67]
	v_mfma_f32_16x16x32_bf16 v[52:55], v[166:169], v[190:193], v[52:55]
	v_mfma_f32_16x16x32_bf16 v[52:55], v[170:173], v[194:197], v[52:55]
	v_mfma_f32_16x16x32_bf16 v[48:51], v[174:177], v[190:193], v[48:51]
	v_mfma_f32_16x16x32_bf16 v[48:51], v[178:181], v[194:197], v[48:51]
	v_mfma_f32_16x16x32_bf16 v[44:47], v[166:169], v[198:201], v[44:47]
	v_mfma_f32_16x16x32_bf16 v[44:47], v[170:173], v[202:205], v[44:47]
	v_mfma_f32_16x16x32_bf16 v[40:43], v[174:177], v[198:201], v[40:43]
	v_mfma_f32_16x16x32_bf16 v[40:43], v[178:181], v[202:205], v[40:43]
	v_mfma_f32_16x16x32_bf16 v[36:39], v[166:169], v[206:209], v[36:39]
	v_mfma_f32_16x16x32_bf16 v[36:39], v[170:173], v[210:213], v[36:39]
	v_mfma_f32_16x16x32_bf16 v[32:35], v[174:177], v[206:209], v[32:35]
	v_mfma_f32_16x16x32_bf16 v[32:35], v[178:181], v[210:213], v[32:35]
	s_setprio 0
	s_waitcnt vmcnt(8)
	s_barrier
	ds_read_b128 v[182:185], v158 offset:16384
	ds_read_b128 v[186:189], v158 offset:17408
	ds_read_b128 v[190:193], v158 offset:18432
	ds_read_b128 v[194:197], v158 offset:19456
	ds_read_b128 v[198:201], v158 offset:20480
	ds_read_b128 v[202:205], v158 offset:21504
	ds_read_b128 v[206:209], v158 offset:22528
	ds_read_b128 v[210:213], v158 offset:23552
	s_add_u32 vcc_lo, s20, 0x404000
	s_addc_u32 vcc_hi, s21, 0
	s_add_i32 m0, s24, 0x10000
	s_nop 0
	global_load_lds_dwordx4 v138, s[20:21]
	s_add_i32 m0, s24, 0x12000
	s_nop 0
	global_load_lds_dwordx4 v142, s[20:21]
	s_add_i32 m0, s24, 0x14000
	s_nop 0
	global_load_lds_dwordx4 v138, vcc
	s_add_i32 m0, s24, 0x16000
	s_nop 0
	global_load_lds_dwordx4 v142, vcc
	s_mov_b32 m0, s24
	s_nop 0
	global_load_lds_dwordx4 v136, s[22:23]
	s_add_i32 m0, s24, 0x2000
	s_nop 0
	global_load_lds_dwordx4 v140, s[22:23]
	s_waitcnt lgkmcnt(0)
	s_setprio 1
	v_mfma_f32_16x16x32_bf16 v[92:95], v[128:131], v[182:185], v[92:95]
	v_mfma_f32_16x16x32_bf16 v[92:95], v[132:135], v[186:189], v[92:95]
	v_mfma_f32_16x16x32_bf16 v[88:91], v[150:153], v[182:185], v[88:91]
	v_mfma_f32_16x16x32_bf16 v[88:91], v[162:165], v[186:189], v[88:91]
	v_mfma_f32_16x16x32_bf16 v[84:87], v[128:131], v[190:193], v[84:87]
	v_mfma_f32_16x16x32_bf16 v[84:87], v[132:135], v[194:197], v[84:87]
	v_mfma_f32_16x16x32_bf16 v[80:83], v[150:153], v[190:193], v[80:83]
	v_mfma_f32_16x16x32_bf16 v[80:83], v[162:165], v[194:197], v[80:83]
	v_mfma_f32_16x16x32_bf16 v[76:79], v[128:131], v[198:201], v[76:79]
	v_mfma_f32_16x16x32_bf16 v[76:79], v[132:135], v[202:205], v[76:79]
	v_mfma_f32_16x16x32_bf16 v[72:75], v[150:153], v[198:201], v[72:75]
	v_mfma_f32_16x16x32_bf16 v[72:75], v[162:165], v[202:205], v[72:75]
	v_mfma_f32_16x16x32_bf16 v[60:63], v[128:131], v[206:209], v[60:63]
	v_mfma_f32_16x16x32_bf16 v[60:63], v[132:135], v[210:213], v[60:63]
	v_mfma_f32_16x16x32_bf16 v[56:59], v[150:153], v[206:209], v[56:59]
	v_mfma_f32_16x16x32_bf16 v[56:59], v[162:165], v[210:213], v[56:59]
	v_mfma_f32_16x16x32_bf16 v[28:31], v[166:169], v[182:185], v[28:31]
	v_mfma_f32_16x16x32_bf16 v[28:31], v[170:173], v[186:189], v[28:31]
	v_mfma_f32_16x16x32_bf16 v[24:27], v[174:177], v[182:185], v[24:27]
	v_mfma_f32_16x16x32_bf16 v[24:27], v[178:181], v[186:189], v[24:27]
	v_mfma_f32_16x16x32_bf16 v[20:23], v[166:169], v[190:193], v[20:23]
	v_mfma_f32_16x16x32_bf16 v[20:23], v[170:173], v[194:197], v[20:23]
	v_mfma_f32_16x16x32_bf16 v[16:19], v[174:177], v[190:193], v[16:19]
	v_mfma_f32_16x16x32_bf16 v[16:19], v[178:181], v[194:197], v[16:19]
	v_mfma_f32_16x16x32_bf16 v[12:15], v[166:169], v[198:201], v[12:15]
	v_mfma_f32_16x16x32_bf16 v[12:15], v[170:173], v[202:205], v[12:15]
	v_mfma_f32_16x16x32_bf16 v[8:11], v[174:177], v[198:201], v[8:11]
	v_mfma_f32_16x16x32_bf16 v[8:11], v[178:181], v[202:205], v[8:11]
	v_mfma_f32_16x16x32_bf16 v[4:7], v[166:169], v[206:209], v[4:7]
	v_mfma_f32_16x16x32_bf16 v[4:7], v[170:173], v[210:213], v[4:7]
	v_mfma_f32_16x16x32_bf16 v[0:3], v[174:177], v[206:209], v[0:3]
	v_mfma_f32_16x16x32_bf16 v[0:3], v[178:181], v[210:213], v[0:3]
	s_setprio 0
	s_waitcnt vmcnt(8)
	s_barrier
; #define PG8_STAGE(bufoff, gbase, voff) do { _Pragma("unroll") for (int _i = 0; _i < 2; ++_i) \
;         __builtin_amdgcn_global_load_lds((const unsigned*)((const char*)(gbase) + (voff)[_i]), (PG8_LAS unsigned*)(lds + (bufoff) + ldsw + _i * 8192), 16, 0, 0); } while (0)
; #define PG8_LDA(dst, b, h) do { _Pragma("unroll") for (int m = 0; m < 4; ++m) _Pragma("unroll") for (int k = 0; k < 2; ++k) dst[m][k] = *(const PG8_LAS bf16x8*)(lds + PG8_SA(b, h) + aoff + m * 2048 + k * 1024); } while (0)
; #define PG8_LDB(dst, b, h) do { _Pragma("unroll") for (int n = 0; n < 2; ++n) _Pragma("unroll") for (int k = 0; k < 2; ++k) dst[n][k] = *(const PG8_LAS bf16x8*)(lds + PG8_SB(b, h) + boff + n * 2048 + k * 1024); } while (0)
; #define PG8_MMA(ai, bj, At, Bt) do { __builtin_amdgcn_s_setprio(1); _Pragma("unroll") for (int m = 0; m < 4; ++m) _Pragma("unroll") for (int n = 0; n < 2; ++n) _Pragma("unroll") for (int k = 0; k < 2; ++k) \
;         acc[ai][bj][m][n] = __builtin_amdgcn_mfma_f32_16x16x32_bf16(Bt[n][k], At[m][k], acc[ai][bj][m][n], 0, 0, 0); __builtin_amdgcn_s_setprio(0); } while (0)
; #define PG8_WAIT_V(n) asm volatile("s_waitcnt vmcnt(" #n ")" ::: "memory")
; #define PG8_WAIT_L(n) asm volatile("s_waitcnt lgkmcnt(" #n ")" ::: "memory")
; #define PG8_BAR __builtin_amdgcn_s_barrier()
; #define PG8_SCHED __builtin_amdgcn_sched_barrier(0)
; template <class Epi, class Sched, bool ALIGN_EPI = false, bool SP2 = false>
; __device__ __forceinline__ void gemm_phase(PG8_LAS unsigned char* lds, const Gemm g, const Sched& S, const Epi& E) {
;     ...
;             PG8_LDB(B0, 1, 0); PG8_LDB(B1, 1, 1); PG8_SCHED; PG8_LDA(At, 1, 0); PG8_STAGE(PG8_SA(0, 1), a2 + hstep, voffA);
;             PG8_WAIT_V(8); PG8_WAIT_L(0); PG8_BAR; PG8_MMA(0, 0, At, B0); PG8_MMA(0, 1, At, B1); PG8_BAR; PG8_SCHED;
;             PG8_LDA(At, 1, 1); PG8_STAGE(PG8_SB(1, 0), b3, voffB); PG8_STAGE(PG8_SB(1, 1), b3 + hstep, voffB); PG8_STAGE(PG8_SA(1, 0), a3, voffA);
;             PG8_WAIT_V(8); PG8_WAIT_L(0); PG8_BAR; PG8_MMA(1, 0, At, B0); PG8_MMA(1, 1, At, B1); PG8_BAR; PG8_SCHED;
	ds_read_b128 v[128:131], v159
	ds_read_b128 v[132:135], v159 offset:1024
	ds_read_b128 v[150:153], v159 offset:2048
	ds_read_b128 v[162:165], v159 offset:3072
	ds_read_b128 v[166:169], v160
	ds_read_b128 v[170:173], v160 offset:1024
	ds_read_b128 v[174:177], v160 offset:2048
	ds_read_b128 v[178:181], v160 offset:3072
	ds_read_b128 v[182:185], v158 offset:32768
	ds_read_b128 v[186:189], v158 offset:33792
	ds_read_b128 v[190:193], v158 offset:34816
	ds_read_b128 v[194:197], v158 offset:35840
	ds_read_b128 v[198:201], v158 offset:36864
	ds_read_b128 v[202:205], v158 offset:37888
	ds_read_b128 v[206:209], v158 offset:38912
	ds_read_b128 v[210:213], v158 offset:39936
	s_add_u32 vcc_lo, s22, 0x404000
	s_addc_u32 vcc_hi, s23, 0
	s_add_i32 m0, s24, 0x4000
	s_nop 0
	global_load_lds_dwordx4 v136, vcc
	s_add_i32 m0, s24, 0x6000
	s_nop 0
	global_load_lds_dwordx4 v140, vcc
	s_waitcnt lgkmcnt(0)
	s_setprio 1
	v_mfma_f32_16x16x32_bf16 v[124:127], v[128:131], v[182:185], v[124:127]
	v_mfma_f32_16x16x32_bf16 v[124:127], v[132:135], v[186:189], v[124:127]
	v_mfma_f32_16x16x32_bf16 v[120:123], v[150:153], v[182:185], v[120:123]
	v_mfma_f32_16x16x32_bf16 v[120:123], v[162:165], v[186:189], v[120:123]
	v_mfma_f32_16x16x32_bf16 v[116:119], v[128:131], v[190:193], v[116:119]
	v_mfma_f32_16x16x32_bf16 v[116:119], v[132:135], v[194:197], v[116:119]
	v_mfma_f32_16x16x32_bf16 v[112:115], v[150:153], v[190:193], v[112:115]
	v_mfma_f32_16x16x32_bf16 v[112:115], v[162:165], v[194:197], v[112:115]
	v_mfma_f32_16x16x32_bf16 v[108:111], v[128:131], v[198:201], v[108:111]
	v_mfma_f32_16x16x32_bf16 v[108:111], v[132:135], v[202:205], v[108:111]
	v_mfma_f32_16x16x32_bf16 v[104:107], v[150:153], v[198:201], v[104:107]
	v_mfma_f32_16x16x32_bf16 v[104:107], v[162:165], v[202:205], v[104:107]
	v_mfma_f32_16x16x32_bf16 v[100:103], v[128:131], v[206:209], v[100:103]
	v_mfma_f32_16x16x32_bf16 v[100:103], v[132:135], v[210:213], v[100:103]
	v_mfma_f32_16x16x32_bf16 v[96:99], v[150:153], v[206:209], v[96:99]
	v_mfma_f32_16x16x32_bf16 v[96:99], v[162:165], v[210:213], v[96:99]
	v_mfma_f32_16x16x32_bf16 v[68:71], v[166:169], v[182:185], v[68:71]
	v_mfma_f32_16x16x32_bf16 v[68:71], v[170:173], v[186:189], v[68:71]
	v_mfma_f32_16x16x32_bf16 v[64:67], v[174:177], v[182:185], v[64:67]
	v_mfma_f32_16x16x32_bf16 v[64:67], v[178:181], v[186:189], v[64:67]
	v_mfma_f32_16x16x32_bf16 v[52:55], v[166:169], v[190:193], v[52:55]
	v_mfma_f32_16x16x32_bf16 v[52:55], v[170:173], v[194:197], v[52:55]
	v_mfma_f32_16x16x32_bf16 v[48:51], v[174:177], v[190:193], v[48:51]
	v_mfma_f32_16x16x32_bf16 v[48:51], v[178:181], v[194:197], v[48:51]
	v_mfma_f32_16x16x32_bf16 v[44:47], v[166:169], v[198:201], v[44:47]
	v_mfma_f32_16x16x32_bf16 v[44:47], v[170:173], v[202:205], v[44:47]
	v_mfma_f32_16x16x32_bf16 v[40:43], v[174:177], v[198:201], v[40:43]
	v_mfma_f32_16x16x32_bf16 v[40:43], v[178:181], v[202:205], v[40:43]
	v_mfma_f32_16x16x32_bf16 v[36:39], v[166:169], v[206:209], v[36:39]
	v_mfma_f32_16x16x32_bf16 v[36:39], v[170:173], v[210:213], v[36:39]
	v_mfma_f32_16x16x32_bf16 v[32:35], v[174:177], v[206:209], v[32:35]
	v_mfma_f32_16x16x32_bf16 v[32:35], v[178:181], v[210:213], v[32:35]
	s_setprio 0
	s_waitcnt vmcnt(8)
	s_barrier
	ds_read_b128 v[182:185], v158 offset:49152
	ds_read_b128 v[186:189], v158 offset:50176
	ds_read_b128 v[190:193], v158 offset:51200
	ds_read_b128 v[194:197], v158 offset:52224
	ds_read_b128 v[198:201], v158 offset:53248
	ds_read_b128 v[202:205], v158 offset:54272
	ds_read_b128 v[206:209], v158 offset:55296
	ds_read_b128 v[210:213], v158 offset:56320
	s_add_u32 s60, s20, 0x80
	s_addc_u32 s61, s21, 0
	s_add_u32 vcc_lo, s60, 0x404000
	s_addc_u32 vcc_hi, s61, 0
	s_add_i32 m0, s24, 0x18000
	s_nop 0
	global_load_lds_dwordx4 v138, s[60:61]
	s_add_i32 m0, s24, 0x1a000
	s_nop 0
	global_load_lds_dwordx4 v142, s[60:61]
	s_add_i32 m0, s24, 0x1c000
	s_nop 0
	global_load_lds_dwordx4 v138, vcc
	s_add_i32 m0, s24, 0x1e000
	s_nop 0
	global_load_lds_dwordx4 v142, vcc
	s_add_u32 s60, s22, 0x80
	s_addc_u32 s61, s23, 0
	s_add_i32 m0, s24, 0x8000
	s_nop 0
	global_load_lds_dwordx4 v136, s[60:61]
	s_add_i32 m0, s24, 0xa000
	s_nop 0
	global_load_lds_dwordx4 v140, s[60:61]
	s_waitcnt lgkmcnt(0)
	s_setprio 1
	v_mfma_f32_16x16x32_bf16 v[92:95], v[128:131], v[182:185], v[92:95]
	v_mfma_f32_16x16x32_bf16 v[92:95], v[132:135], v[186:189], v[92:95]
	v_mfma_f32_16x16x32_bf16 v[88:91], v[150:153], v[182:185], v[88:91]
	v_mfma_f32_16x16x32_bf16 v[88:91], v[162:165], v[186:189], v[88:91]
	v_mfma_f32_16x16x32_bf16 v[84:87], v[128:131], v[190:193], v[84:87]
	v_mfma_f32_16x16x32_bf16 v[84:87], v[132:135], v[194:197], v[84:87]
	v_mfma_f32_16x16x32_bf16 v[80:83], v[150:153], v[190:193], v[80:83]
	v_mfma_f32_16x16x32_bf16 v[80:83], v[162:165], v[194:197], v[80:83]
	v_mfma_f32_16x16x32_bf16 v[76:79], v[128:131], v[198:201], v[76:79]
	v_mfma_f32_16x16x32_bf16 v[76:79], v[132:135], v[202:205], v[76:79]
	v_mfma_f32_16x16x32_bf16 v[72:75], v[150:153], v[198:201], v[72:75]
	v_mfma_f32_16x16x32_bf16 v[72:75], v[162:165], v[202:205], v[72:75]
	v_mfma_f32_16x16x32_bf16 v[60:63], v[128:131], v[206:209], v[60:63]
	v_mfma_f32_16x16x32_bf16 v[60:63], v[132:135], v[210:213], v[60:63]
	v_mfma_f32_16x16x32_bf16 v[56:59], v[150:153], v[206:209], v[56:59]
	v_mfma_f32_16x16x32_bf16 v[56:59], v[162:165], v[210:213], v[56:59]
	v_mfma_f32_16x16x32_bf16 v[28:31], v[166:169], v[182:185], v[28:31]
	v_mfma_f32_16x16x32_bf16 v[28:31], v[170:173], v[186:189], v[28:31]
	v_mfma_f32_16x16x32_bf16 v[24:27], v[174:177], v[182:185], v[24:27]
	v_mfma_f32_16x16x32_bf16 v[24:27], v[178:181], v[186:189], v[24:27]
	v_mfma_f32_16x16x32_bf16 v[20:23], v[166:169], v[190:193], v[20:23]
	v_mfma_f32_16x16x32_bf16 v[20:23], v[170:173], v[194:197], v[20:23]
	v_mfma_f32_16x16x32_bf16 v[16:19], v[174:177], v[190:193], v[16:19]
	v_mfma_f32_16x16x32_bf16 v[16:19], v[178:181], v[194:197], v[16:19]
	v_mfma_f32_16x16x32_bf16 v[12:15], v[166:169], v[198:201], v[12:15]
	v_mfma_f32_16x16x32_bf16 v[12:15], v[170:173], v[202:205], v[12:15]
	v_mfma_f32_16x16x32_bf16 v[8:11], v[174:177], v[198:201], v[8:11]
	v_mfma_f32_16x16x32_bf16 v[8:11], v[178:181], v[202:205], v[8:11]
	v_mfma_f32_16x16x32_bf16 v[4:7], v[166:169], v[206:209], v[4:7]
	v_mfma_f32_16x16x32_bf16 v[4:7], v[170:173], v[210:213], v[4:7]
	v_mfma_f32_16x16x32_bf16 v[0:3], v[174:177], v[206:209], v[0:3]
	v_mfma_f32_16x16x32_bf16 v[0:3], v[178:181], v[210:213], v[0:3]
	s_setprio 0
	s_waitcnt vmcnt(8)
	s_barrier
	s_add_i32 s59, s59, 2
	s_add_u32 s18, s18, 0x100
	s_addc_u32 s19, s19, 0
	s_add_u32 s57, s57, 0x100
	s_addc_u32 s58, s58, 0
	s_cmpk_gt_u32 s59, 0xfd
	s_cbranch_scc0 .LBB0_1321
	s_branch .Lf2_exit
; #define PG8_STAGE(bufoff, gbase, voff) do { _Pragma("unroll") for (int _i = 0; _i < 2; ++_i) \
;         __builtin_amdgcn_global_load_lds((const unsigned*)((const char*)(gbase) + (voff)[_i]), (PG8_LAS unsigned*)(lds + (bufoff) + ldsw + _i * 8192), 16, 0, 0); } while (0)
; #define PG8_LDA(dst, b, h) do { _Pragma("unroll") for (int m = 0; m < 4; ++m) _Pragma("unroll") for (int k = 0; k < 2; ++k) dst[m][k] = *(const PG8_LAS bf16x8*)(lds + PG8_SA(b, h) + aoff + m * 2048 + k * 1024); } while (0)
; #define PG8_LDB(dst, b, h) do { _Pragma("unroll") for (int n = 0; n < 2; ++n) _Pragma("unroll") for (int k = 0; k < 2; ++k) dst[n][k] = *(const PG8_LAS bf16x8*)(lds + PG8_SB(b, h) + boff + n * 2048 + k * 1024); } while (0)
; #define PG8_MMA(ai, bj, At, Bt) do { __builtin_amdgcn_s_setprio(1); _Pragma("unroll") for (int m = 0; m < 4; ++m) _Pragma("unroll") for (int n = 0; n < 2; ++n) _Pragma("unroll") for (int k = 0; k < 2; ++k) \
;         acc[ai][bj][m][n] = __builtin_amdgcn_mfma_f32_16x16x32_bf16(Bt[n][k], At[m][k], acc[ai][bj][m][n], 0, 0, 0); __builtin_amdgcn_s_setprio(0); } while (0)
; #define PG8_WAIT_V(n) asm volatile("s_waitcnt vmcnt(" #n ")" ::: "memory")
; #define PG8_WAIT_L(n) asm volatile("s_waitcnt lgkmcnt(" #n ")" ::: "memory")
; #define PG8_BAR __builtin_amdgcn_s_barrier()
; #define PG8_SCHED __builtin_amdgcn_sched_barrier(0)
; template <class Epi, class Sched, bool ALIGN_EPI = false, bool SP2 = false>
; __device__ __forceinline__ void gemm_phase(PG8_LAS unsigned char* lds, const Gemm g, const Sched& S, const Epi& E) {
;     ...
;             if constexpr (SP2) {
;             PG8_LDB(B0, 0, 0); PG8_LDB(B1, 0, 1); PG8_SCHED; PG8_LDA(At, 0, 0); PG8_STAGE(PG8_SA(1, 1), a1 + hstep, voffA);
;             PG8_WAIT_V(8); PG8_WAIT_L(0); PG8_BAR; PG8_MMA(0, 0, At, B0); PG8_MMA(0, 1, At, B1); PG8_BAR; PG8_SCHED;
.Lf2_h1:
	ds_read_b128 v[128:131], v156
	ds_read_b128 v[132:135], v156 offset:1024
	ds_read_b128 v[150:153], v156 offset:2048
	ds_read_b128 v[162:165], v156 offset:3072
	ds_read_b128 v[166:169], v157
	ds_read_b128 v[170:173], v157 offset:1024
	ds_read_b128 v[174:177], v157 offset:2048
	ds_read_b128 v[178:181], v157 offset:3072
	s_add_u32 s20, s18, 0xffbfc080
	s_addc_u32 s21, s19, -1
	s_cmpk_eq_i32 s59, 0xfc
	s_cselect_b32 s23, s7, s21
	s_cselect_b32 s22, s6, s20
	s_cselect_b32 s21, s17, s58
	s_cselect_b32 s20, s16, s57
	ds_read_b128 v[182:185], v158
	ds_read_b128 v[186:189], v158 offset:1024
	ds_read_b128 v[190:193], v158 offset:2048
	ds_read_b128 v[194:197], v158 offset:3072
	ds_read_b128 v[198:201], v158 offset:4096
	ds_read_b128 v[202:205], v158 offset:5120
	ds_read_b128 v[206:209], v158 offset:6144
	ds_read_b128 v[210:213], v158 offset:7168
	s_add_i32 m0, s24, 0xc000
	s_nop 0
	global_load_lds_dwordx4 v136, s[18:19]
	s_add_i32 m0, s24, 0xe000
	s_nop 0
	global_load_lds_dwordx4 v140, s[18:19]
	s_sleep 2
	s_waitcnt lgkmcnt(0)
	s_waitcnt vmcnt(8)
	s_barrier
	s_setprio 2
	v_mfma_f32_16x16x32_bf16 v[124:127], v[128:131], v[182:185], v[124:127]
	v_mfma_f32_16x16x32_bf16 v[124:127], v[132:135], v[186:189], v[124:127]
	v_mfma_f32_16x16x32_bf16 v[120:123], v[150:153], v[182:185], v[120:123]
	v_mfma_f32_16x16x32_bf16 v[120:123], v[162:165], v[186:189], v[120:123]
	v_mfma_f32_16x16x32_bf16 v[116:119], v[128:131], v[190:193], v[116:119]
	v_mfma_f32_16x16x32_bf16 v[116:119], v[132:135], v[194:197], v[116:119]
	v_mfma_f32_16x16x32_bf16 v[112:115], v[150:153], v[190:193], v[112:115]
	v_mfma_f32_16x16x32_bf16 v[112:115], v[162:165], v[194:197], v[112:115]
	v_mfma_f32_16x16x32_bf16 v[108:111], v[128:131], v[198:201], v[108:111]
	v_mfma_f32_16x16x32_bf16 v[108:111], v[132:135], v[202:205], v[108:111]
	v_mfma_f32_16x16x32_bf16 v[104:107], v[150:153], v[198:201], v[104:107]
	v_mfma_f32_16x16x32_bf16 v[104:107], v[162:165], v[202:205], v[104:107]
	v_mfma_f32_16x16x32_bf16 v[100:103], v[128:131], v[206:209], v[100:103]
	v_mfma_f32_16x16x32_bf16 v[100:103], v[132:135], v[210:213], v[100:103]
	v_mfma_f32_16x16x32_bf16 v[96:99], v[150:153], v[206:209], v[96:99]
	v_mfma_f32_16x16x32_bf16 v[96:99], v[162:165], v[210:213], v[96:99]
	v_mfma_f32_16x16x32_bf16 v[68:71], v[166:169], v[182:185], v[68:71]
	v_mfma_f32_16x16x32_bf16 v[68:71], v[170:173], v[186:189], v[68:71]
	v_mfma_f32_16x16x32_bf16 v[64:67], v[174:177], v[182:185], v[64:67]
	v_mfma_f32_16x16x32_bf16 v[64:67], v[178:181], v[186:189], v[64:67]
	v_mfma_f32_16x16x32_bf16 v[52:55], v[166:169], v[190:193], v[52:55]
	v_mfma_f32_16x16x32_bf16 v[52:55], v[170:173], v[194:197], v[52:55]
	v_mfma_f32_16x16x32_bf16 v[48:51], v[174:177], v[190:193], v[48:51]
	v_mfma_f32_16x16x32_bf16 v[48:51], v[178:181], v[194:197], v[48:51]
	v_mfma_f32_16x16x32_bf16 v[44:47], v[166:169], v[198:201], v[44:47]
	v_mfma_f32_16x16x32_bf16 v[44:47], v[170:173], v[202:205], v[44:47]
	v_mfma_f32_16x16x32_bf16 v[40:43], v[174:177], v[198:201], v[40:43]
	v_mfma_f32_16x16x32_bf16 v[40:43], v[178:181], v[202:205], v[40:43]
	v_mfma_f32_16x16x32_bf16 v[36:39], v[166:169], v[206:209], v[36:39]
	v_mfma_f32_16x16x32_bf16 v[36:39], v[170:173], v[210:213], v[36:39]
	v_mfma_f32_16x16x32_bf16 v[32:35], v[174:177], v[206:209], v[32:35]
	v_mfma_f32_16x16x32_bf16 v[32:35], v[178:181], v[210:213], v[32:35]
	s_setprio 0
	ds_read_b128 v[182:185], v158 offset:16384
	ds_read_b128 v[186:189], v158 offset:17408
	ds_read_b128 v[190:193], v158 offset:18432
	ds_read_b128 v[194:197], v158 offset:19456
	ds_read_b128 v[198:201], v158 offset:20480
	ds_read_b128 v[202:205], v158 offset:21504
	ds_read_b128 v[206:209], v158 offset:22528
	ds_read_b128 v[210:213], v158 offset:23552
	s_add_u32 vcc_lo, s20, 0x404000
	s_addc_u32 vcc_hi, s21, 0
	s_add_i32 m0, s24, 0x10000
	s_nop 0
	global_load_lds_dwordx4 v138, s[20:21]
	s_add_i32 m0, s24, 0x12000
	s_nop 0
	global_load_lds_dwordx4 v142, s[20:21]
	s_add_i32 m0, s24, 0x14000
	s_nop 0
	global_load_lds_dwordx4 v138, vcc
	s_add_i32 m0, s24, 0x16000
	s_nop 0
	global_load_lds_dwordx4 v142, vcc
	s_mov_b32 m0, s24
	s_nop 0
	global_load_lds_dwordx4 v136, s[22:23]
	s_add_i32 m0, s24, 0x2000
	s_nop 0
	global_load_lds_dwordx4 v140, s[22:23]
	s_sleep 2
	s_waitcnt lgkmcnt(0)
	s_waitcnt vmcnt(8)
	s_barrier
; #define PG8_STAGE(bufoff, gbase, voff) do { _Pragma("unroll") for (int _i = 0; _i < 2; ++_i) \
;         __builtin_amdgcn_global_load_lds((const unsigned*)((const char*)(gbase) + (voff)[_i]), (PG8_LAS unsigned*)(lds + (bufoff) + ldsw + _i * 8192), 16, 0, 0); } while (0)
; #define PG8_LDA(dst, b, h) do { _Pragma("unroll") for (int m = 0; m < 4; ++m) _Pragma("unroll") for (int k = 0; k < 2; ++k) dst[m][k] = *(const PG8_LAS bf16x8*)(lds + PG8_SA(b, h) + aoff + m * 2048 + k * 1024); } while (0)
; #define PG8_LDB(dst, b, h) do { _Pragma("unroll") for (int n = 0; n < 2; ++n) _Pragma("unroll") for (int k = 0; k < 2; ++k) dst[n][k] = *(const PG8_LAS bf16x8*)(lds + PG8_SB(b, h) + boff + n * 2048 + k * 1024); } while (0)
; #define PG8_MMA(ai, bj, At, Bt) do { __builtin_amdgcn_s_setprio(1); _Pragma("unroll") for (int m = 0; m < 4; ++m) _Pragma("unroll") for (int n = 0; n < 2; ++n) _Pragma("unroll") for (int k = 0; k < 2; ++k) \
;         acc[ai][bj][m][n] = __builtin_amdgcn_mfma_f32_16x16x32_bf16(Bt[n][k], At[m][k], acc[ai][bj][m][n], 0, 0, 0); __builtin_amdgcn_s_setprio(0); } while (0)
; #define PG8_WAIT_V(n) asm volatile("s_waitcnt vmcnt(" #n ")" ::: "memory")
; #define PG8_WAIT_L(n) asm volatile("s_waitcnt lgkmcnt(" #n ")" ::: "memory")
; #define PG8_BAR __builtin_amdgcn_s_barrier()
; #define PG8_SCHED __builtin_amdgcn_sched_barrier(0)
; template <class Epi, class Sched, bool ALIGN_EPI = false, bool SP2 = false>
; __device__ __forceinline__ void gemm_phase(PG8_LAS unsigned char* lds, const Gemm g, const Sched& S, const Epi& E) {
;     ...
;             PG8_WAIT_V(8); PG8_WAIT_L(0); PG8_BAR; PG8_MMA(0, 0, At, B0); PG8_MMA(0, 1, At, B1); PG8_BAR; PG8_SCHED;
;             PG8_LDA(At, 0, 1); PG8_STAGE(PG8_SB(0, 0), b2, voffB); PG8_STAGE(PG8_SB(0, 1), b2 + hstep, voffB); PG8_STAGE(PG8_SA(0, 0), a2, voffA);
;             PG8_WAIT_V(8); PG8_WAIT_L(0); PG8_BAR; PG8_MMA(1, 0, At, B0); PG8_MMA(1, 1, At, B1); PG8_BAR; PG8_SCHED;
;             PG8_LDB(B0, 1, 0); PG8_LDB(B1, 1, 1); PG8_SCHED; PG8_LDA(At, 1, 0); PG8_STAGE(PG8_SA(0, 1), a2 + hstep, voffA);
	s_setprio 2
	v_mfma_f32_16x16x32_bf16 v[92:95], v[128:131], v[182:185], v[92:95]
	v_mfma_f32_16x16x32_bf16 v[92:95], v[132:135], v[186:189], v[92:95]
	v_mfma_f32_16x16x32_bf16 v[88:91], v[150:153], v[182:185], v[88:91]
	v_mfma_f32_16x16x32_bf16 v[88:91], v[162:165], v[186:189], v[88:91]
	v_mfma_f32_16x16x32_bf16 v[84:87], v[128:131], v[190:193], v[84:87]
	v_mfma_f32_16x16x32_bf16 v[84:87], v[132:135], v[194:197], v[84:87]
	v_mfma_f32_16x16x32_bf16 v[80:83], v[150:153], v[190:193], v[80:83]
	v_mfma_f32_16x16x32_bf16 v[80:83], v[162:165], v[194:197], v[80:83]
	v_mfma_f32_16x16x32_bf16 v[76:79], v[128:131], v[198:201], v[76:79]
	v_mfma_f32_16x16x32_bf16 v[76:79], v[132:135], v[202:205], v[76:79]
	v_mfma_f32_16x16x32_bf16 v[72:75], v[150:153], v[198:201], v[72:75]
	v_mfma_f32_16x16x32_bf16 v[72:75], v[162:165], v[202:205], v[72:75]
	v_mfma_f32_16x16x32_bf16 v[60:63], v[128:131], v[206:209], v[60:63]
	v_mfma_f32_16x16x32_bf16 v[60:63], v[132:135], v[210:213], v[60:63]
	v_mfma_f32_16x16x32_bf16 v[56:59], v[150:153], v[206:209], v[56:59]
	v_mfma_f32_16x16x32_bf16 v[56:59], v[162:165], v[210:213], v[56:59]
	v_mfma_f32_16x16x32_bf16 v[28:31], v[166:169], v[182:185], v[28:31]
	v_mfma_f32_16x16x32_bf16 v[28:31], v[170:173], v[186:189], v[28:31]
	v_mfma_f32_16x16x32_bf16 v[24:27], v[174:177], v[182:185], v[24:27]
	v_mfma_f32_16x16x32_bf16 v[24:27], v[178:181], v[186:189], v[24:27]
	v_mfma_f32_16x16x32_bf16 v[20:23], v[166:169], v[190:193], v[20:23]
	v_mfma_f32_16x16x32_bf16 v[20:23], v[170:173], v[194:197], v[20:23]
	v_mfma_f32_16x16x32_bf16 v[16:19], v[174:177], v[190:193], v[16:19]
	v_mfma_f32_16x16x32_bf16 v[16:19], v[178:181], v[194:197], v[16:19]
	v_mfma_f32_16x16x32_bf16 v[12:15], v[166:169], v[198:201], v[12:15]
	v_mfma_f32_16x16x32_bf16 v[12:15], v[170:173], v[202:205], v[12:15]
	v_mfma_f32_16x16x32_bf16 v[8:11], v[174:177], v[198:201], v[8:11]
	v_mfma_f32_16x16x32_bf16 v[8:11], v[178:181], v[202:205], v[8:11]
	v_mfma_f32_16x16x32_bf16 v[4:7], v[166:169], v[206:209], v[4:7]
	v_mfma_f32_16x16x32_bf16 v[4:7], v[170:173], v[210:213], v[4:7]
	v_mfma_f32_16x16x32_bf16 v[0:3], v[174:177], v[206:209], v[0:3]
	v_mfma_f32_16x16x32_bf16 v[0:3], v[178:181], v[210:213], v[0:3]
	s_setprio 0
	ds_read_b128 v[128:131], v159
	ds_read_b128 v[132:135], v159 offset:1024
	ds_read_b128 v[150:153], v159 offset:2048
	ds_read_b128 v[162:165], v159 offset:3072
	ds_read_b128 v[166:169], v160
	ds_read_b128 v[170:173], v160 offset:1024
	ds_read_b128 v[174:177], v160 offset:2048
	ds_read_b128 v[178:181], v160 offset:3072
	ds_read_b128 v[182:185], v158 offset:32768
	ds_read_b128 v[186:189], v158 offset:33792
	ds_read_b128 v[190:193], v158 offset:34816
	ds_read_b128 v[194:197], v158 offset:35840
	ds_read_b128 v[198:201], v158 offset:36864
	ds_read_b128 v[202:205], v158 offset:37888
	ds_read_b128 v[206:209], v158 offset:38912
	ds_read_b128 v[210:213], v158 offset:39936
	s_add_u32 vcc_lo, s22, 0x404000
	s_addc_u32 vcc_hi, s23, 0
	s_add_i32 m0, s24, 0x4000
	s_nop 0
	global_load_lds_dwordx4 v136, vcc
	s_add_i32 m0, s24, 0x6000
	s_nop 0
	global_load_lds_dwordx4 v140, vcc
	s_sleep 2
	s_waitcnt lgkmcnt(0)
	s_waitcnt vmcnt(8)
	s_barrier
; #define PG8_STAGE(bufoff, gbase, voff) do { _Pragma("unroll") for (int _i = 0; _i < 2; ++_i) \
;         __builtin_amdgcn_global_load_lds((const unsigned*)((const char*)(gbase) + (voff)[_i]), (PG8_LAS unsigned*)(lds + (bufoff) + ldsw + _i * 8192), 16, 0, 0); } while (0)
; #define PG8_LDA(dst, b, h) do { _Pragma("unroll") for (int m = 0; m < 4; ++m) _Pragma("unroll") for (int k = 0; k < 2; ++k) dst[m][k] = *(const PG8_LAS bf16x8*)(lds + PG8_SA(b, h) + aoff + m * 2048 + k * 1024); } while (0)
; #define PG8_LDB(dst, b, h) do { _Pragma("unroll") for (int n = 0; n < 2; ++n) _Pragma("unroll") for (int k = 0; k < 2; ++k) dst[n][k] = *(const PG8_LAS bf16x8*)(lds + PG8_SB(b, h) + boff + n * 2048 + k * 1024); } while (0)
; #define PG8_MMA(ai, bj, At, Bt) do { __builtin_amdgcn_s_setprio(1); _Pragma("unroll") for (int m = 0; m < 4; ++m) _Pragma("unroll") for (int n = 0; n < 2; ++n) _Pragma("unroll") for (int k = 0; k < 2; ++k) \
;         acc[ai][bj][m][n] = __builtin_amdgcn_mfma_f32_16x16x32_bf16(Bt[n][k], At[m][k], acc[ai][bj][m][n], 0, 0, 0); __builtin_amdgcn_s_setprio(0); } while (0)
; #define PG8_WAIT_V(n) asm volatile("s_waitcnt vmcnt(" #n ")" ::: "memory")
; #define PG8_WAIT_L(n) asm volatile("s_waitcnt lgkmcnt(" #n ")" ::: "memory")
; #define PG8_BAR __builtin_amdgcn_s_barrier()
; #define PG8_SCHED __builtin_amdgcn_sched_barrier(0)
; template <class Epi, class Sched, bool ALIGN_EPI = false, bool SP2 = false>
; __device__ __forceinline__ void gemm_phase(PG8_LAS unsigned char* lds, const Gemm g, const Sched& S, const Epi& E) {
;     ...
;             PG8_LDB(B0, 1, 0); PG8_LDB(B1, 1, 1); PG8_SCHED; PG8_LDA(At, 1, 0); PG8_STAGE(PG8_SA(0, 1), a2 + hstep, voffA);
;             PG8_WAIT_V(8); PG8_WAIT_L(0); PG8_BAR; PG8_MMA(0, 0, At, B0); PG8_MMA(0, 1, At, B1); PG8_BAR; PG8_SCHED;
;             PG8_LDA(At, 1, 1); PG8_STAGE(PG8_SB(1, 0), b3, voffB); PG8_STAGE(PG8_SB(1, 1), b3 + hstep, voffB); PG8_STAGE(PG8_SA(1, 0), a3, voffA);
;             PG8_WAIT_V(8); PG8_WAIT_L(0); PG8_BAR; PG8_MMA(1, 0, At, B0); PG8_MMA(1, 1, At, B1); PG8_BAR; PG8_SCHED;
	s_setprio 2
	v_mfma_f32_16x16x32_bf16 v[124:127], v[128:131], v[182:185], v[124:127]
	v_mfma_f32_16x16x32_bf16 v[124:127], v[132:135], v[186:189], v[124:127]
	v_mfma_f32_16x16x32_bf16 v[120:123], v[150:153], v[182:185], v[120:123]
	v_mfma_f32_16x16x32_bf16 v[120:123], v[162:165], v[186:189], v[120:123]
	v_mfma_f32_16x16x32_bf16 v[116:119], v[128:131], v[190:193], v[116:119]
	v_mfma_f32_16x16x32_bf16 v[116:119], v[132:135], v[194:197], v[116:119]
	v_mfma_f32_16x16x32_bf16 v[112:115], v[150:153], v[190:193], v[112:115]
	v_mfma_f32_16x16x32_bf16 v[112:115], v[162:165], v[194:197], v[112:115]
	v_mfma_f32_16x16x32_bf16 v[108:111], v[128:131], v[198:201], v[108:111]
	v_mfma_f32_16x16x32_bf16 v[108:111], v[132:135], v[202:205], v[108:111]
	v_mfma_f32_16x16x32_bf16 v[104:107], v[150:153], v[198:201], v[104:107]
	v_mfma_f32_16x16x32_bf16 v[104:107], v[162:165], v[202:205], v[104:107]
	v_mfma_f32_16x16x32_bf16 v[100:103], v[128:131], v[206:209], v[100:103]
	v_mfma_f32_16x16x32_bf16 v[100:103], v[132:135], v[210:213], v[100:103]
	v_mfma_f32_16x16x32_bf16 v[96:99], v[150:153], v[206:209], v[96:99]
	v_mfma_f32_16x16x32_bf16 v[96:99], v[162:165], v[210:213], v[96:99]
	v_mfma_f32_16x16x32_bf16 v[68:71], v[166:169], v[182:185], v[68:71]
	v_mfma_f32_16x16x32_bf16 v[68:71], v[170:173], v[186:189], v[68:71]
	v_mfma_f32_16x16x32_bf16 v[64:67], v[174:177], v[182:185], v[64:67]
	v_mfma_f32_16x16x32_bf16 v[64:67], v[178:181], v[186:189], v[64:67]
	v_mfma_f32_16x16x32_bf16 v[52:55], v[166:169], v[190:193], v[52:55]
	v_mfma_f32_16x16x32_bf16 v[52:55], v[170:173], v[194:197], v[52:55]
	v_mfma_f32_16x16x32_bf16 v[48:51], v[174:177], v[190:193], v[48:51]
	v_mfma_f32_16x16x32_bf16 v[48:51], v[178:181], v[194:197], v[48:51]
	v_mfma_f32_16x16x32_bf16 v[44:47], v[166:169], v[198:201], v[44:47]
	v_mfma_f32_16x16x32_bf16 v[44:47], v[170:173], v[202:205], v[44:47]
	v_mfma_f32_16x16x32_bf16 v[40:43], v[174:177], v[198:201], v[40:43]
	v_mfma_f32_16x16x32_bf16 v[40:43], v[178:181], v[202:205], v[40:43]
	v_mfma_f32_16x16x32_bf16 v[36:39], v[166:169], v[206:209], v[36:39]
	v_mfma_f32_16x16x32_bf16 v[36:39], v[170:173], v[210:213], v[36:39]
	v_mfma_f32_16x16x32_bf16 v[32:35], v[174:177], v[206:209], v[32:35]
	v_mfma_f32_16x16x32_bf16 v[32:35], v[178:181], v[210:213], v[32:35]
	s_setprio 0
	ds_read_b128 v[182:185], v158 offset:49152
	ds_read_b128 v[186:189], v158 offset:50176
	ds_read_b128 v[190:193], v158 offset:51200
	ds_read_b128 v[194:197], v158 offset:52224
	ds_read_b128 v[198:201], v158 offset:53248
	ds_read_b128 v[202:205], v158 offset:54272
	ds_read_b128 v[206:209], v158 offset:55296
	ds_read_b128 v[210:213], v158 offset:56320
	s_add_u32 s60, s20, 0x80
	s_addc_u32 s61, s21, 0
	s_add_u32 vcc_lo, s60, 0x404000
	s_addc_u32 vcc_hi, s61, 0
	s_add_i32 m0, s24, 0x18000
	s_nop 0
	global_load_lds_dwordx4 v138, s[60:61]
	s_add_i32 m0, s24, 0x1a000
	s_nop 0
	global_load_lds_dwordx4 v142, s[60:61]
	s_add_i32 m0, s24, 0x1c000
	s_nop 0
	global_load_lds_dwordx4 v138, vcc
	s_add_i32 m0, s24, 0x1e000
	s_nop 0
	global_load_lds_dwordx4 v142, vcc
	s_add_u32 s60, s22, 0x80
	s_addc_u32 s61, s23, 0
	s_add_i32 m0, s24, 0x8000
	s_nop 0
	global_load_lds_dwordx4 v136, s[60:61]
	s_add_i32 m0, s24, 0xa000
	s_nop 0
	global_load_lds_dwordx4 v140, s[60:61]
	s_sleep 2
	s_waitcnt lgkmcnt(0)
	s_waitcnt vmcnt(8)
	s_barrier
	s_setprio 2
	v_mfma_f32_16x16x32_bf16 v[92:95], v[128:131], v[182:185], v[92:95]
	v_mfma_f32_16x16x32_bf16 v[92:95], v[132:135], v[186:189], v[92:95]
	v_mfma_f32_16x16x32_bf16 v[88:91], v[150:153], v[182:185], v[88:91]
	v_mfma_f32_16x16x32_bf16 v[88:91], v[162:165], v[186:189], v[88:91]
	v_mfma_f32_16x16x32_bf16 v[84:87], v[128:131], v[190:193], v[84:87]
	v_mfma_f32_16x16x32_bf16 v[84:87], v[132:135], v[194:197], v[84:87]
	v_mfma_f32_16x16x32_bf16 v[80:83], v[150:153], v[190:193], v[80:83]
	v_mfma_f32_16x16x32_bf16 v[80:83], v[162:165], v[194:197], v[80:83]
	v_mfma_f32_16x16x32_bf16 v[76:79], v[128:131], v[198:201], v[76:79]
	v_mfma_f32_16x16x32_bf16 v[76:79], v[132:135], v[202:205], v[76:79]
	v_mfma_f32_16x16x32_bf16 v[72:75], v[150:153], v[198:201], v[72:75]
	v_mfma_f32_16x16x32_bf16 v[72:75], v[162:165], v[202:205], v[72:75]
	v_mfma_f32_16x16x32_bf16 v[60:63], v[128:131], v[206:209], v[60:63]
	v_mfma_f32_16x16x32_bf16 v[60:63], v[132:135], v[210:213], v[60:63]
	v_mfma_f32_16x16x32_bf16 v[56:59], v[150:153], v[206:209], v[56:59]
	v_mfma_f32_16x16x32_bf16 v[56:59], v[162:165], v[210:213], v[56:59]
	v_mfma_f32_16x16x32_bf16 v[28:31], v[166:169], v[182:185], v[28:31]
	v_mfma_f32_16x16x32_bf16 v[28:31], v[170:173], v[186:189], v[28:31]
	v_mfma_f32_16x16x32_bf16 v[24:27], v[174:177], v[182:185], v[24:27]
	v_mfma_f32_16x16x32_bf16 v[24:27], v[178:181], v[186:189], v[24:27]
	v_mfma_f32_16x16x32_bf16 v[20:23], v[166:169], v[190:193], v[20:23]
	v_mfma_f32_16x16x32_bf16 v[20:23], v[170:173], v[194:197], v[20:23]
	v_mfma_f32_16x16x32_bf16 v[16:19], v[174:177], v[190:193], v[16:19]
	v_mfma_f32_16x16x32_bf16 v[16:19], v[178:181], v[194:197], v[16:19]
	v_mfma_f32_16x16x32_bf16 v[12:15], v[166:169], v[198:201], v[12:15]
	v_mfma_f32_16x16x32_bf16 v[12:15], v[170:173], v[202:205], v[12:15]
	v_mfma_f32_16x16x32_bf16 v[8:11], v[174:177], v[198:201], v[8:11]
	v_mfma_f32_16x16x32_bf16 v[8:11], v[178:181], v[202:205], v[8:11]
	v_mfma_f32_16x16x32_bf16 v[4:7], v[166:169], v[206:209], v[4:7]
	v_mfma_f32_16x16x32_bf16 v[4:7], v[170:173], v[210:213], v[4:7]
	v_mfma_f32_16x16x32_bf16 v[0:3], v[174:177], v[206:209], v[0:3]
	v_mfma_f32_16x16x32_bf16 v[0:3], v[178:181], v[210:213], v[0:3]
	s_setprio 0
	s_add_i32 s59, s59, 2
	s_add_u32 s18, s18, 0x100
	s_addc_u32 s19, s19, 0
	s_add_u32 s57, s57, 0x100
	s_addc_u32 s58, s58, 0
	s_cmpk_gt_u32 s59, 0xfd
	s_cbranch_scc0 .Lf2_h1
